# QK-norm loops: integer bit-trick bf16 packs replaced by v_cvt_pk_bf16_f32 (same RNE rounding, 280 fewer VALU ops per loop set)
# baseline (speedup 1.0000x reference)
.LBB0_320:
	s_mul_hi_i32 s28, s23, 0x55555556
	s_lshr_b32 s0, s28, 31
	s_add_i32 s28, s28, s0
	s_lshr_b32 s1, s28, 7
	s_and_b32 s0, s28, 0xff
	s_and_b32 s1, s1, 56
	s_cmpk_lt_u32 s28, 0x2000
	s_cselect_b32 s18, 4, 0
	s_or_b32 s1, s18, s1
	s_bfe_u32 s18, s28, 0x20008
	s_or_b32 s1, s1, s18
	s_lshl_b32 s1, s1, 8
	s_or_b32 s29, s1, s0
	s_mul_i32 s0, s28, 3
	s_sub_i32 s0, s23, s0
	s_waitcnt vmcnt(3)
	v_lshl_or_b32 v18, s0, 3, v80
	s_mul_i32 s0, s29, 0x4200
	s_add_u32 s18, s14, s0
	s_addc_u32 s19, s15, 0
	s_add_i32 s27, s72, s23
	s_min_i32 s0, s27, 0xbfff
	s_mul_hi_i32 s1, s0, 0x55555556
	s_lshr_b32 s25, s1, 31
	s_add_i32 s1, s1, s25
	s_lshr_b32 s26, s1, 7
	s_and_b32 s25, s1, 0xff
	s_and_b32 s26, s26, 56
	s_cmpk_lt_u32 s1, 0x2000
	s_cselect_b32 s30, 4, 0
	v_mul_i32_i24_e32 v18, 0x60, v18
	s_or_b32 s26, s30, s26
	s_bfe_u32 s30, s1, 0x20008
	v_ashrrev_i32_e32 v19, 31, v18
	s_or_b32 s26, s26, s30
	v_lshl_add_u64 v[18:19], v[18:19], 1, s[18:19]
	v_lshlrev_b32_e32 v204, 1, v60
	s_lshl_b32 s26, s26, 8
	s_mul_i32 s1, s1, 3
	v_lshl_add_u64 v[18:19], v[18:19], 0, v[204:205]
	s_or_b32 s25, s26, s25
	s_sub_i32 s0, s0, s1
	global_load_dwordx2 v[74:75], v[18:19], off offset:16
	global_load_dwordx4 v[70:73], v[18:19], off
	v_lshl_or_b32 v18, s0, 3, v80
	s_mulk_i32 s25, 0x4200
	s_movk_i32 s34, 0x60
	s_add_u32 s0, s14, s25
	v_mul_lo_u32 v18, v18, s34
	s_addc_u32 s1, s15, 0
	v_ashrrev_i32_e32 v19, 31, v18
	s_add_i32 s26, s91, s23
	v_lshl_add_u64 v[18:19], v[18:19], 1, s[0:1]
	s_min_i32 s0, s26, 0xbfff
	s_mul_hi_i32 s1, s0, 0x55555556
	s_lshr_b32 s25, s1, 31
	s_add_i32 s1, s1, s25
	s_lshr_b32 s30, s1, 7
	s_and_b32 s25, s1, 0xff
	s_and_b32 s30, s30, 56
	s_cmpk_lt_u32 s1, 0x2000
	s_cselect_b32 s31, 4, 0
	s_or_b32 s30, s31, s30
	s_bfe_u32 s31, s1, 0x20008
	s_or_b32 s30, s30, s31
	s_lshl_b32 s30, s30, 8
	s_mul_i32 s1, s1, 3
	v_lshl_add_u64 v[18:19], v[18:19], 0, v[204:205]
	s_or_b32 s25, s30, s25
	s_sub_i32 s0, s0, s1
	global_load_dwordx2 v[68:69], v[18:19], off offset:16
	global_load_dwordx4 v[56:59], v[18:19], off
	v_lshl_or_b32 v18, s0, 3, v80
	s_mulk_i32 s25, 0x4200
	s_add_u32 s0, s14, s25
	v_mul_lo_u32 v18, v18, s34
	s_addc_u32 s1, s15, 0
	v_ashrrev_i32_e32 v19, 31, v18
	v_lshl_add_u64 v[18:19], v[18:19], 1, s[0:1]
	v_readlane_b32 s0, v253, 25
	s_add_i32 s25, s0, s23
	s_min_i32 s0, s25, 0xbfff
	s_mul_hi_i32 s1, s0, 0x55555556
	s_lshr_b32 s30, s1, 31
	s_add_i32 s1, s1, s30
	s_lshr_b32 s31, s1, 7
	s_and_b32 s30, s1, 0xff
	s_and_b32 s31, s31, 56
	s_cmpk_lt_u32 s1, 0x2000
	s_cselect_b32 s33, 4, 0
	s_or_b32 s31, s33, s31
	s_bfe_u32 s33, s1, 0x20008
	s_or_b32 s31, s31, s33
	s_lshl_b32 s31, s31, 8
	s_mul_i32 s1, s1, 3
	v_lshl_add_u64 v[18:19], v[18:19], 0, v[204:205]
	s_or_b32 s30, s31, s30
	s_sub_i32 s0, s0, s1
	global_load_dwordx2 v[66:67], v[18:19], off offset:16
	global_load_dwordx4 v[52:55], v[18:19], off
	v_lshl_or_b32 v18, s0, 3, v80
	s_mulk_i32 s30, 0x4200
	s_add_u32 s0, s14, s30
	v_mul_lo_u32 v18, v18, s34
	s_addc_u32 s1, s15, 0
	v_ashrrev_i32_e32 v19, 31, v18
	v_lshl_add_u64 v[18:19], v[18:19], 1, s[0:1]
	s_waitcnt vmcnt(8)
	v_lshl_add_u64 v[48:49], v[18:19], 0, v[204:205]
	global_load_dwordx2 v[18:19], v[48:49], off offset:16
	s_nop 0
	global_load_dwordx4 v[48:51], v[48:49], off
	s_mul_i32 s0, s28, 0xffffffe8
	v_add_u32_e32 v21, s0, v83
	s_and_b32 s0, s29, s20
	v_cvt_f32_u32_e32 v23, s0
	s_waitcnt vmcnt(6)
	v_lshlrev_b32_e32 v86, 16, v70
	v_and_b32_e32 v88, 0xffff0000, v70
	v_lshlrev_b32_e32 v78, 16, v72
	v_and_b32_e32 v76, 0xffff0000, v72
	v_lshlrev_b32_e32 v72, 16, v74
	v_and_b32_e32 v70, 0xffff0000, v74
	v_mul_f32_e32 v74, v26, v23
	v_fract_f32_e32 v74, v74
	v_fmac_f32_e32 v74, v27, v23
	v_cos_f32_e32 v118, v74
	v_sin_f32_e32 v124, v74
	v_mul_f32_e32 v74, v28, v23
	v_fract_f32_e32 v74, v74
	v_fmac_f32_e32 v74, v29, v23
	v_cos_f32_e32 v112, v74
	v_sin_f32_e32 v114, v74
	v_mul_f32_e32 v74, v30, v23
	v_fract_f32_e32 v74, v74
	v_fmac_f32_e32 v74, v31, v23
	v_cos_f32_e32 v119, v74
	v_sin_f32_e32 v125, v74
	v_mul_f32_e32 v74, v32, v23
	v_fract_f32_e32 v74, v74
	v_fmac_f32_e32 v74, v33, v23
	v_cos_f32_e32 v126, v74
	v_sin_f32_e32 v127, v74
	v_mul_f32_e32 v74, v34, v23
	v_fract_f32_e32 v74, v74
	v_fmac_f32_e32 v74, v35, v23
	v_cos_f32_e32 v128, v74
	v_sin_f32_e32 v129, v74
	v_mul_f32_e32 v74, v36, v23
	v_fract_f32_e32 v74, v74
	v_fmac_f32_e32 v74, v37, v23
	v_cos_f32_e32 v130, v74
	v_sin_f32_e32 v131, v74
	v_mul_f32_e32 v74, v38, v23
	v_cmp_gt_i32_e64 s[0:1], 12, v21
	v_mul_f32_e32 v21, v24, v23
	v_fract_f32_e32 v74, v74
	v_fract_f32_e32 v21, v21
	v_fmac_f32_e32 v74, v39, v23
	v_fmac_f32_e32 v21, v25, v23
	v_cos_f32_e32 v132, v74
	v_sin_f32_e32 v133, v74
	v_mul_f32_e32 v74, v40, v23
	v_cos_f32_e32 v85, v21
	v_sin_f32_e32 v21, v21
	v_fract_f32_e32 v74, v74
	v_fmac_f32_e32 v74, v41, v23
	v_lshlrev_b32_e32 v87, 16, v71
	v_and_b32_e32 v89, 0xffff0000, v71
	v_cos_f32_e32 v98, v74
	v_sin_f32_e32 v100, v74
	v_mul_f32_e32 v74, v42, v23
	v_fract_f32_e32 v74, v74
	v_pk_mul_f32 v[106:107], v[86:87], v[86:87]
	v_pk_mul_f32 v[108:109], v[88:89], v[88:89]
	v_fmac_f32_e32 v74, v43, v23
	v_cndmask_b32_e64 v115, 0, v114, s[4:5]
	v_cndmask_b32_e64 v114, 0, v21, s[4:5]
	v_add_f32_e32 v21, v106, v108
	v_cos_f32_e32 v102, v74
	v_sin_f32_e32 v104, v74
	v_mul_f32_e32 v74, v44, v23
	v_mov_b32_e32 v120, v78
	v_mov_b32_e32 v121, v76
	v_add_f32_e32 v21, v21, v107
	v_lshlrev_b32_e32 v79, 16, v73
	v_and_b32_e32 v77, 0xffff0000, v73
	v_fract_f32_e32 v74, v74
	v_pk_mul_f32 v[120:121], v[120:121], v[120:121]
	v_add_f32_e32 v21, v21, v109
	v_fmac_f32_e32 v74, v45, v23
	v_mov_b32_e32 v122, v79
	v_mov_b32_e32 v123, v77
	v_add_f32_e32 v21, v21, v120
	v_cos_f32_e32 v99, v74
	v_sin_f32_e32 v101, v74
	v_mul_f32_e32 v74, v46, v23
	v_pk_mul_f32 v[122:123], v[122:123], v[122:123]
	v_add_f32_e32 v21, v21, v121
	v_fract_f32_e32 v74, v74
	v_mov_b32_e32 v90, v72
	v_mov_b32_e32 v91, v70
	v_add_f32_e32 v21, v21, v122
	v_lshlrev_b32_e32 v73, 16, v75
	v_and_b32_e32 v71, 0xffff0000, v75
	v_fmac_f32_e32 v74, v47, v23
	v_pk_mul_f32 v[90:91], v[90:91], v[90:91]
	v_add_f32_e32 v21, v21, v123
	v_cos_f32_e32 v23, v74
	v_mov_b32_e32 v92, v73
	v_mov_b32_e32 v93, v71
	v_add_f32_e32 v21, v21, v90
	v_pk_mul_f32 v[92:93], v[92:93], v[92:93]
	v_add_f32_e32 v21, v21, v91
	v_add_f32_e32 v21, v21, v92
	v_add_f32_e32 v21, v21, v93
	v_cndmask_b32_e64 v103, 1.0, v23, s[4:5]
	ds_swizzle_b32 v23, v21 offset:swizzle(SWAP,1)
	v_cndmask_b32_e64 v64, 1.0, v225, s[0:1]
	v_cndmask_b32_e64 v95, v1, v7, s[0:1]
	v_cndmask_b32_e64 v94, v0, v12, s[0:1]
	v_cndmask_b32_e64 v97, v61, v13, s[0:1]
	s_waitcnt lgkmcnt(0)
	v_add_f32_e32 v21, v21, v23
	ds_swizzle_b32 v23, v21 offset:swizzle(SWAP,2)
	v_cndmask_b32_e64 v96, v62, v6, s[0:1]
	v_cndmask_b32_e64 v111, v3, v9, s[0:1]
	v_cndmask_b32_e64 v110, v8, v20, s[0:1]
	v_cndmask_b32_e64 v117, v63, v15, s[0:1]
	s_waitcnt lgkmcnt(0)
	v_add_f32_e32 v21, v21, v23
	ds_swizzle_b32 v23, v21 offset:swizzle(SWAP,4)
	v_cndmask_b32_e64 v116, v2, v14, s[0:1]
	v_cndmask_b32_e64 v93, v5, v11, s[0:1]
	v_cndmask_b32_e64 v92, v4, v16, s[0:1]
	v_cndmask_b32_e64 v121, v65, v17, s[0:1]
	s_waitcnt lgkmcnt(0)
	v_add_f32_e32 v21, v21, v23
	v_cndmask_b32_e64 v120, v10, v22, s[0:1]
	v_fmamk_f32 v21, v21, 0x3c2aaaab, v224
	s_mov_b32 s0, 0x800000
	v_mul_f32_e32 v23, 0x4b800000, v21
	v_cmp_gt_f32_e64 s[0:1], s0, v21
	v_cndmask_b32_e64 v106, 1.0, v126, s[4:5]
	v_cndmask_b32_e64 v113, 1.0, v112, s[4:5]
	v_cndmask_b32_e64 v21, v21, v23, s[0:1]
	v_rsq_f32_e32 v21, v21
	v_cndmask_b32_e64 v112, 1.0, v85, s[4:5]
	v_cndmask_b32_e64 v91, 0, v125, s[4:5]
	v_cndmask_b32_e64 v90, 0, v124, s[4:5]
	v_mul_f32_e32 v23, 0x45800000, v21
	v_cndmask_b32_e64 v126, v21, v23, s[0:1]
	v_pk_mul_f32 v[86:87], v[126:127], v[86:87] op_sel_hi:[0,1]
	v_pk_mul_f32 v[86:87], v[86:87], v[110:111]
	ds_swizzle_b32 v21, v87 offset:swizzle(SWAP,1)
	ds_swizzle_b32 v23, v86 offset:swizzle(SWAP,1)
	v_pk_mul_f32 v[88:89], v[126:127], v[88:89] op_sel_hi:[0,1]
	v_pk_mul_f32 v[88:89], v[88:89], v[116:117]
	ds_swizzle_b32 v85, v88 offset:swizzle(SWAP,1)
	s_waitcnt lgkmcnt(2)
	v_cndmask_b32_e64 v111, v21, -v21, vcc
	ds_swizzle_b32 v21, v89 offset:swizzle(SWAP,1)
	s_waitcnt lgkmcnt(2)
	v_cndmask_b32_e64 v110, v23, -v23, vcc
	v_pk_mul_f32 v[78:79], v[126:127], v[78:79] op_sel_hi:[0,1]
	v_pk_mul_f32 v[110:111], v[110:111], v[114:115]
	v_pk_mul_f32 v[78:79], v[78:79], v[92:93]
	v_pk_fma_f32 v[86:87], v[86:87], v[112:113], v[110:111]
	s_waitcnt lgkmcnt(0)
	v_cndmask_b32_e64 v111, v21, -v21, vcc
	ds_swizzle_b32 v21, v79 offset:swizzle(SWAP,1)
	v_cndmask_b32_e64 v110, v85, -v85, vcc
	ds_swizzle_b32 v23, v78 offset:swizzle(SWAP,1)
	v_pk_mul_f32 v[76:77], v[126:127], v[76:77] op_sel_hi:[0,1]
	v_cndmask_b32_e64 v119, 1.0, v119, s[4:5]
	v_cndmask_b32_e64 v118, 1.0, v118, s[4:5]
	v_pk_mul_f32 v[90:91], v[110:111], v[90:91]
	v_pk_mul_f32 v[76:77], v[76:77], v[120:121]
	v_pk_fma_f32 v[88:89], v[88:89], v[118:119], v[90:91]
	s_waitcnt lgkmcnt(1)
	v_cndmask_b32_e64 v91, v21, -v21, vcc
	ds_swizzle_b32 v21, v77 offset:swizzle(SWAP,1)
	v_cndmask_b32_e64 v109, 0, v131, s[4:5]
	v_cndmask_b32_e64 v108, 0, v127, s[4:5]
	ds_swizzle_b32 v85, v76 offset:swizzle(SWAP,1)
	s_waitcnt lgkmcnt(2)
	v_cndmask_b32_e64 v90, v23, -v23, vcc
	v_pk_mul_f32 v[72:73], v[126:127], v[72:73] op_sel_hi:[0,1]
	v_cndmask_b32_e64 v107, 1.0, v130, s[4:5]
	v_pk_mul_f32 v[90:91], v[90:91], v[108:109]
	v_pk_mul_f32 v[72:73], v[72:73], v[94:95]
	v_pk_fma_f32 v[78:79], v[78:79], v[106:107], v[90:91]
	s_waitcnt lgkmcnt(1)
	v_cndmask_b32_e64 v91, v21, -v21, vcc
	ds_swizzle_b32 v21, v73 offset:swizzle(SWAP,1)
	ds_swizzle_b32 v23, v72 offset:swizzle(SWAP,1)
	v_cndmask_b32_e64 v125, 0, v133, s[4:5]
	v_cndmask_b32_e64 v124, 0, v129, s[4:5]
	s_waitcnt lgkmcnt(2)
	v_cndmask_b32_e64 v90, v85, -v85, vcc
	v_pk_mul_f32 v[70:71], v[126:127], v[70:71] op_sel_hi:[0,1]
	v_cndmask_b32_e64 v123, 1.0, v132, s[4:5]
	v_cndmask_b32_e64 v122, 1.0, v128, s[4:5]
	v_pk_mul_f32 v[90:91], v[90:91], v[124:125]
	v_pk_mul_f32 v[70:71], v[70:71], v[96:97]
	v_pk_fma_f32 v[76:77], v[76:77], v[122:123], v[90:91]
	ds_swizzle_b32 v85, v70 offset:swizzle(SWAP,1)
	s_waitcnt lgkmcnt(2)
	v_cndmask_b32_e64 v91, v21, -v21, vcc
	ds_swizzle_b32 v21, v71 offset:swizzle(SWAP,1)
	v_sin_f32_e32 v105, v74
	v_cndmask_b32_e64 v101, 0, v101, s[4:5]
	v_cndmask_b32_e64 v100, 0, v100, s[4:5]
	s_waitcnt lgkmcnt(2)
	v_cndmask_b32_e64 v90, v23, -v23, vcc
	v_cndmask_b32_e64 v99, 1.0, v99, s[4:5]
	v_cndmask_b32_e64 v98, 1.0, v98, s[4:5]
	v_pk_mul_f32 v[90:91], v[90:91], v[100:101]
	v_cndmask_b32_e64 v105, 0, v105, s[4:5]
	v_pk_fma_f32 v[72:73], v[72:73], v[98:99], v[90:91]
	v_cndmask_b32_e64 v104, 0, v104, s[4:5]
	v_pk_mul_f32 v[90:91], v[64:65], v[72:73] op_sel_hi:[0,1]
	s_waitcnt lgkmcnt(0)
	v_cndmask_b32_e64 v73, v21, -v21, vcc
	v_cndmask_b32_e64 v72, v85, -v85, vcc
	v_cndmask_b32_e64 v102, 1.0, v102, s[4:5]
	v_pk_mul_f32 v[72:73], v[72:73], v[104:105]
	v_pk_mul_f32 v[86:87], v[64:65], v[86:87] op_sel_hi:[0,1]
	v_pk_mul_f32 v[76:77], v[64:65], v[76:77] op_sel_hi:[0,1]
	v_pk_fma_f32 v[70:71], v[70:71], v[102:103], v[72:73]
	v_pk_mul_f32 v[88:89], v[64:65], v[88:89] op_sel_hi:[0,1]
	v_pk_mul_f32 v[78:79], v[64:65], v[78:79] op_sel_hi:[0,1]
	v_pk_mul_f32 v[92:93], v[64:65], v[70:71] op_sel_hi:[0,1]
	v_cvt_pk_bf16_f32 v70, v86, v88
	v_cvt_pk_bf16_f32 v71, v87, v89
	v_cvt_pk_bf16_f32 v72, v78, v76
	v_cvt_pk_bf16_f32 v73, v79, v77
	v_cvt_pk_bf16_f32 v76, v90, v92
	v_cvt_pk_bf16_f32 v77, v91, v93
	s_mulk_i32 s28, 0xf700
	v_add_u32_e32 v74, s28, v84
	s_mov_b32 s0, 0xffff0000
	v_ashrrev_i32_e32 v75, 31, v74
	v_lshl_add_u64 v[74:75], v[74:75], 1, s[18:19]
	v_lshl_add_u64 v[74:75], v[74:75], 0, v[204:205]
	global_store_dwordx4 v[74:75], v[70:73], off
	global_store_dwordx2 v[74:75], v[76:77], off offset:16
	s_cmp_gt_i32 s27, 0xbfff
	s_cbranch_scc1 .LBB0_322
	s_mul_hi_i32 s0, s27, 0x55555556
	s_lshr_b32 s1, s0, 31
	s_add_i32 s0, s0, s1
	s_lshr_b32 s1, s0, 7
	s_and_b32 s1, s1, 56
	s_cmpk_lt_u32 s0, 0x2000
	s_cselect_b32 s18, 4, 0
	s_or_b32 s1, s18, s1
	s_bfe_u32 s18, s0, 0x20008
	s_or_b32 s1, s1, s18
	s_mul_i32 s18, s0, 3
	s_lshl_b32 s1, s1, 8
	s_sub_i32 s18, s27, s18
	s_and_b32 s0, s0, 0xff
	v_lshl_or_b32 v21, s18, 3, v80
	s_or_b32 s18, s1, s0
	s_and_b32 s0, s18, s20
	v_cvt_f32_u32_e32 v23, s0
	s_waitcnt vmcnt(6)
	v_lshlrev_b32_e32 v74, 16, v58
	v_and_b32_e32 v72, 0xffff0000, v58
	v_lshlrev_b32_e32 v70, 16, v68
	v_and_b32_e32 v58, 0xffff0000, v68
	v_mul_f32_e32 v68, v26, v23
	v_fract_f32_e32 v68, v68
	v_fmac_f32_e32 v68, v27, v23
	v_cos_f32_e32 v85, v68
	v_sin_f32_e32 v120, v68
	v_mul_f32_e32 v68, v28, v23
	v_fract_f32_e32 v68, v68
	v_fmac_f32_e32 v68, v29, v23
	v_cos_f32_e32 v108, v68
	v_sin_f32_e32 v110, v68
	v_mul_f32_e32 v68, v30, v23
	v_fract_f32_e32 v68, v68
	v_fmac_f32_e32 v68, v31, v23
	v_cos_f32_e32 v114, v68
	v_sin_f32_e32 v121, v68
	v_mul_f32_e32 v68, v32, v23
	v_fract_f32_e32 v68, v68
	v_fmac_f32_e32 v68, v33, v23
	v_cos_f32_e32 v122, v68
	v_sin_f32_e32 v123, v68
	v_mul_f32_e32 v68, v34, v23
	v_fract_f32_e32 v68, v68
	v_fmac_f32_e32 v68, v35, v23
	v_cos_f32_e32 v124, v68
	v_sin_f32_e32 v125, v68
	v_mul_f32_e32 v68, v36, v23
	v_fract_f32_e32 v68, v68
	v_fmac_f32_e32 v68, v37, v23
	v_cos_f32_e32 v126, v68
	v_sin_f32_e32 v127, v68
	v_mul_f32_e32 v68, v38, v23
	v_fract_f32_e32 v68, v68
	v_fmac_f32_e32 v68, v39, v23
	v_cos_f32_e32 v128, v68
	v_sin_f32_e32 v129, v68
	v_mul_f32_e32 v68, v40, v23
	v_fract_f32_e32 v68, v68
	v_fmac_f32_e32 v68, v41, v23
	v_cos_f32_e32 v94, v68
	v_sin_f32_e32 v96, v68
	v_mul_f32_e32 v68, v42, v23
	v_fract_f32_e32 v68, v68
	v_fmac_f32_e32 v68, v43, v23
	v_cos_f32_e32 v98, v68
	v_sin_f32_e32 v100, v68
	v_mul_f32_e32 v68, v44, v23
	v_fract_f32_e32 v68, v68
	v_fmac_f32_e32 v68, v45, v23
	v_cos_f32_e32 v95, v68
	v_sin_f32_e32 v97, v68
	v_mul_f32_e32 v68, v46, v23
	v_lshlrev_b32_e32 v78, 16, v56
	v_and_b32_e32 v76, 0xffff0000, v56
	v_lshlrev_b32_e32 v79, 16, v57
	v_and_b32_e32 v77, 0xffff0000, v57
	v_mul_f32_e32 v57, v24, v23
	v_fract_f32_e32 v68, v68
	v_fract_f32_e32 v57, v57
	v_fmac_f32_e32 v68, v47, v23
	s_movk_i32 s27, 0x60
	v_pk_mul_f32 v[102:103], v[78:79], v[78:79]
	v_pk_mul_f32 v[104:105], v[76:77], v[76:77]
	v_cmp_gt_i32_e64 s[0:1], 12, v21
	v_fmac_f32_e32 v57, v25, v23
	v_cos_f32_e32 v23, v68
	v_sin_f32_e32 v101, v68
	v_mul_lo_u32 v68, v21, s27
	v_add_f32_e32 v21, v102, v104
	v_mov_b32_e32 v116, v74
	v_mov_b32_e32 v117, v72
	v_add_f32_e32 v21, v21, v103
	v_lshlrev_b32_e32 v75, 16, v59
	v_and_b32_e32 v73, 0xffff0000, v59
	v_pk_mul_f32 v[116:117], v[116:117], v[116:117]
	v_add_f32_e32 v21, v21, v105
	v_mov_b32_e32 v118, v75
	v_mov_b32_e32 v119, v73
	v_add_f32_e32 v21, v21, v116
	v_pk_mul_f32 v[118:119], v[118:119], v[118:119]
	v_add_f32_e32 v21, v21, v117
	v_mov_b32_e32 v86, v70
	v_mov_b32_e32 v87, v58
	v_add_f32_e32 v21, v21, v118
	v_lshlrev_b32_e32 v71, 16, v69
	v_and_b32_e32 v59, 0xffff0000, v69
	v_pk_mul_f32 v[86:87], v[86:87], v[86:87]
	v_add_f32_e32 v21, v21, v119
	v_mov_b32_e32 v88, v71
	v_mov_b32_e32 v89, v59
	v_add_f32_e32 v21, v21, v86
	v_pk_mul_f32 v[88:89], v[88:89], v[88:89]
	v_add_f32_e32 v21, v21, v87
	v_add_f32_e32 v21, v21, v88
	v_add_f32_e32 v21, v21, v89
	v_cndmask_b32_e64 v99, 1.0, v23, s[4:5]
	ds_swizzle_b32 v23, v21 offset:swizzle(SWAP,1)
	v_cndmask_b32_e64 v56, 1.0, v225, s[0:1]
	v_cndmask_b32_e64 v91, v1, v7, s[0:1]
	v_cndmask_b32_e64 v90, v0, v12, s[0:1]
	v_cndmask_b32_e64 v93, v61, v13, s[0:1]
	s_waitcnt lgkmcnt(0)
	v_add_f32_e32 v21, v21, v23
	ds_swizzle_b32 v23, v21 offset:swizzle(SWAP,2)
	v_cndmask_b32_e64 v92, v62, v6, s[0:1]
	v_cndmask_b32_e64 v107, v3, v9, s[0:1]
	v_cndmask_b32_e64 v106, v8, v20, s[0:1]
	v_cndmask_b32_e64 v113, v63, v15, s[0:1]
	s_waitcnt lgkmcnt(0)
	v_add_f32_e32 v21, v21, v23
	ds_swizzle_b32 v23, v21 offset:swizzle(SWAP,4)
	v_cndmask_b32_e64 v112, v2, v14, s[0:1]
	v_cndmask_b32_e64 v89, v5, v11, s[0:1]
	v_cndmask_b32_e64 v88, v4, v16, s[0:1]
	v_cndmask_b32_e64 v117, v65, v17, s[0:1]
	s_waitcnt lgkmcnt(0)
	v_add_f32_e32 v21, v21, v23
	v_cndmask_b32_e64 v116, v10, v22, s[0:1]
	v_fmamk_f32 v21, v21, 0x3c2aaaab, v224
	s_mov_b32 s0, 0x800000
	v_mul_f32_e32 v23, 0x4b800000, v21
	v_cmp_gt_f32_e64 s[0:1], s0, v21
	v_cos_f32_e32 v64, v57
	v_cndmask_b32_e64 v109, 1.0, v108, s[4:5]
	v_cndmask_b32_e64 v21, v21, v23, s[0:1]
	v_rsq_f32_e32 v21, v21
	v_cndmask_b32_e64 v108, 1.0, v64, s[4:5]
	v_sin_f32_e32 v57, v57
	v_cndmask_b32_e64 v111, 0, v110, s[4:5]
	v_mul_f32_e32 v23, 0x45800000, v21
	v_cndmask_b32_e64 v64, v21, v23, s[0:1]
	v_pk_mul_f32 v[78:79], v[64:65], v[78:79] op_sel_hi:[0,1]
	v_pk_mul_f32 v[78:79], v[78:79], v[106:107]
	ds_swizzle_b32 v21, v79 offset:swizzle(SWAP,1)
	ds_swizzle_b32 v23, v78 offset:swizzle(SWAP,1)
	v_pk_mul_f32 v[76:77], v[64:65], v[76:77] op_sel_hi:[0,1]
	v_pk_mul_f32 v[76:77], v[76:77], v[112:113]
	v_cndmask_b32_e64 v110, 0, v57, s[4:5]
	s_waitcnt lgkmcnt(1)
	v_cndmask_b32_e64 v107, v21, -v21, vcc
	ds_swizzle_b32 v21, v77 offset:swizzle(SWAP,1)
	ds_swizzle_b32 v57, v76 offset:swizzle(SWAP,1)
	s_waitcnt lgkmcnt(2)
	v_cndmask_b32_e64 v106, v23, -v23, vcc
	v_pk_mul_f32 v[74:75], v[64:65], v[74:75] op_sel_hi:[0,1]
	v_pk_mul_f32 v[106:107], v[106:107], v[110:111]
	v_pk_mul_f32 v[74:75], v[74:75], v[88:89]
	v_pk_fma_f32 v[78:79], v[78:79], v[108:109], v[106:107]
	s_waitcnt lgkmcnt(1)
	v_cndmask_b32_e64 v107, v21, -v21, vcc
	ds_swizzle_b32 v21, v75 offset:swizzle(SWAP,1)
	v_cndmask_b32_e64 v87, 0, v121, s[4:5]
	v_cndmask_b32_e64 v86, 0, v120, s[4:5]
	s_waitcnt lgkmcnt(1)
	v_cndmask_b32_e64 v106, v57, -v57, vcc
	ds_swizzle_b32 v23, v74 offset:swizzle(SWAP,1)
	v_pk_mul_f32 v[72:73], v[64:65], v[72:73] op_sel_hi:[0,1]
	v_cndmask_b32_e64 v115, 1.0, v114, s[4:5]
	v_cndmask_b32_e64 v114, 1.0, v85, s[4:5]
	v_pk_mul_f32 v[86:87], v[106:107], v[86:87]
	v_pk_mul_f32 v[72:73], v[72:73], v[116:117]
	v_pk_fma_f32 v[76:77], v[76:77], v[114:115], v[86:87]
	s_waitcnt lgkmcnt(1)
	v_cndmask_b32_e64 v87, v21, -v21, vcc
	ds_swizzle_b32 v21, v73 offset:swizzle(SWAP,1)
	v_pk_mul_f32 v[78:79], v[56:57], v[78:79] op_sel_hi:[0,1]
	v_pk_mul_f32 v[76:77], v[56:57], v[76:77] op_sel_hi:[0,1]
	ds_swizzle_b32 v57, v72 offset:swizzle(SWAP,1)
	v_cndmask_b32_e64 v105, 0, v127, s[4:5]
	v_cndmask_b32_e64 v104, 0, v123, s[4:5]
	s_waitcnt lgkmcnt(2)
	v_cndmask_b32_e64 v86, v23, -v23, vcc
	v_pk_mul_f32 v[70:71], v[64:65], v[70:71] op_sel_hi:[0,1]
	v_cndmask_b32_e64 v103, 1.0, v126, s[4:5]
	v_cndmask_b32_e64 v102, 1.0, v122, s[4:5]
	v_pk_mul_f32 v[86:87], v[86:87], v[104:105]
	v_pk_mul_f32 v[70:71], v[70:71], v[90:91]
	v_pk_fma_f32 v[74:75], v[74:75], v[102:103], v[86:87]
	s_waitcnt lgkmcnt(1)
	v_cndmask_b32_e64 v87, v21, -v21, vcc
	ds_swizzle_b32 v21, v71 offset:swizzle(SWAP,1)
	v_cndmask_b32_e64 v121, 0, v129, s[4:5]
	v_cndmask_b32_e64 v120, 0, v125, s[4:5]
	s_waitcnt lgkmcnt(1)
	v_cndmask_b32_e64 v86, v57, -v57, vcc
	v_cndmask_b32_e64 v119, 1.0, v128, s[4:5]
	v_cndmask_b32_e64 v118, 1.0, v124, s[4:5]
	v_pk_mul_f32 v[86:87], v[86:87], v[120:121]
	ds_swizzle_b32 v23, v70 offset:swizzle(SWAP,1)
	v_pk_mul_f32 v[58:59], v[64:65], v[58:59] op_sel_hi:[0,1]
	v_pk_fma_f32 v[72:73], v[72:73], v[118:119], v[86:87]
	v_pk_mul_f32 v[58:59], v[58:59], v[92:93]
	v_pk_mul_f32 v[74:75], v[56:57], v[74:75] op_sel_hi:[0,1]
	v_pk_mul_f32 v[72:73], v[56:57], v[72:73] op_sel_hi:[0,1]
	ds_swizzle_b32 v57, v58 offset:swizzle(SWAP,1)
	s_waitcnt lgkmcnt(2)
	v_cndmask_b32_e64 v87, v21, -v21, vcc
	ds_swizzle_b32 v21, v59 offset:swizzle(SWAP,1)
	v_cndmask_b32_e64 v97, 0, v97, s[4:5]
	v_cndmask_b32_e64 v96, 0, v96, s[4:5]
	s_waitcnt lgkmcnt(2)
	v_cndmask_b32_e64 v86, v23, -v23, vcc
	v_cndmask_b32_e64 v95, 1.0, v95, s[4:5]
	v_cndmask_b32_e64 v94, 1.0, v94, s[4:5]
	v_pk_mul_f32 v[86:87], v[86:87], v[96:97]
	v_cndmask_b32_e64 v101, 0, v101, s[4:5]
	v_cndmask_b32_e64 v100, 0, v100, s[4:5]
	v_pk_fma_f32 v[70:71], v[70:71], v[94:95], v[86:87]
	s_waitcnt lgkmcnt(0)
	v_cndmask_b32_e64 v87, v21, -v21, vcc
	v_cndmask_b32_e64 v86, v57, -v57, vcc
	v_cndmask_b32_e64 v98, 1.0, v98, s[4:5]
	v_pk_mul_f32 v[86:87], v[86:87], v[100:101]
	v_pk_mul_f32 v[70:71], v[56:57], v[70:71] op_sel_hi:[0,1]
	v_pk_fma_f32 v[58:59], v[58:59], v[98:99], v[86:87]
	v_pk_mul_f32 v[86:87], v[56:57], v[58:59] op_sel_hi:[0,1]
	v_cvt_pk_bf16_f32 v56, v78, v76
	v_cvt_pk_bf16_f32 v57, v79, v77
	v_cvt_pk_bf16_f32 v58, v74, v72
	v_cvt_pk_bf16_f32 v59, v75, v73
	v_cvt_pk_bf16_f32 v70, v70, v86
	v_cvt_pk_bf16_f32 v71, v71, v87
	s_mulk_i32 s18, 0x4200
	s_mov_b32 s0, 0xffff0000
	s_add_u32 s18, s14, s18
	s_addc_u32 s19, s15, 0
	v_ashrrev_i32_e32 v69, 31, v68
	v_lshl_add_u64 v[68:69], v[68:69], 1, s[18:19]
	v_lshl_add_u64 v[68:69], v[68:69], 0, v[204:205]
	global_store_dwordx4 v[68:69], v[56:59], off
	global_store_dwordx2 v[68:69], v[70:71], off offset:16
.LBB0_322:
	s_cmp_gt_i32 s26, 0xbfff
	s_cbranch_scc1 .LBB0_324
	s_mul_hi_i32 s0, s26, 0x55555556
	s_lshr_b32 s1, s0, 31
	s_add_i32 s0, s0, s1
	s_lshr_b32 s1, s0, 7
	s_and_b32 s1, s1, 56
	s_cmpk_lt_u32 s0, 0x2000
	s_cselect_b32 s18, 4, 0
	s_or_b32 s1, s18, s1
	s_bfe_u32 s18, s0, 0x20008
	s_or_b32 s1, s1, s18
	s_mul_i32 s18, s0, 3
	s_lshl_b32 s1, s1, 8
	s_sub_i32 s18, s26, s18
	s_and_b32 s0, s0, 0xff
	v_lshl_or_b32 v21, s18, 3, v80
	s_or_b32 s18, s1, s0
	s_and_b32 s0, s18, s20
	v_cvt_f32_u32_e32 v23, s0
	s_waitcnt vmcnt(4)
	v_lshlrev_b32_e32 v68, 16, v54
	v_and_b32_e32 v58, 0xffff0000, v54
	v_lshlrev_b32_e32 v56, 16, v66
	v_and_b32_e32 v54, 0xffff0000, v66
	v_mul_f32_e32 v66, v26, v23
	v_fract_f32_e32 v66, v66
	v_fmac_f32_e32 v66, v27, v23
	v_cos_f32_e32 v85, v66
	v_sin_f32_e32 v114, v66
	v_mul_f32_e32 v66, v28, v23
	v_fract_f32_e32 v66, v66
	v_fmac_f32_e32 v66, v29, v23
	v_cos_f32_e32 v102, v66
	v_sin_f32_e32 v104, v66
	v_mul_f32_e32 v66, v30, v23
	v_fract_f32_e32 v66, v66
	v_fmac_f32_e32 v66, v31, v23
	v_cos_f32_e32 v108, v66
	v_sin_f32_e32 v115, v66
	v_mul_f32_e32 v66, v32, v23
	v_fract_f32_e32 v66, v66
	v_fmac_f32_e32 v66, v33, v23
	v_cos_f32_e32 v116, v66
	v_sin_f32_e32 v117, v66
	v_mul_f32_e32 v66, v34, v23
	v_fract_f32_e32 v66, v66
	v_fmac_f32_e32 v66, v35, v23
	v_cos_f32_e32 v118, v66
	v_sin_f32_e32 v119, v66
	v_mul_f32_e32 v66, v36, v23
	v_fract_f32_e32 v66, v66
	v_fmac_f32_e32 v66, v37, v23
	v_cos_f32_e32 v120, v66
	v_sin_f32_e32 v121, v66
	v_mul_f32_e32 v66, v38, v23
	v_fract_f32_e32 v66, v66
	v_fmac_f32_e32 v66, v39, v23
	v_cos_f32_e32 v122, v66
	v_sin_f32_e32 v123, v66
	v_mul_f32_e32 v66, v40, v23
	v_fract_f32_e32 v66, v66
	v_fmac_f32_e32 v66, v41, v23
	v_cos_f32_e32 v88, v66
	v_sin_f32_e32 v90, v66
	v_mul_f32_e32 v66, v42, v23
	v_fract_f32_e32 v66, v66
	v_fmac_f32_e32 v66, v43, v23
	v_cos_f32_e32 v92, v66
	v_sin_f32_e32 v94, v66
	v_mul_f32_e32 v66, v44, v23
	v_fract_f32_e32 v66, v66
	v_fmac_f32_e32 v66, v45, v23
	v_cos_f32_e32 v89, v66
	v_sin_f32_e32 v91, v66
	v_mul_f32_e32 v66, v46, v23
	v_lshlrev_b32_e32 v72, 16, v52
	v_and_b32_e32 v70, 0xffff0000, v52
	v_lshlrev_b32_e32 v73, 16, v53
	v_and_b32_e32 v71, 0xffff0000, v53
	v_mul_f32_e32 v53, v24, v23
	v_fract_f32_e32 v66, v66
	v_fract_f32_e32 v53, v53
	v_fmac_f32_e32 v66, v47, v23
	s_movk_i32 s26, 0x60
	v_pk_mul_f32 v[96:97], v[72:73], v[72:73]
	v_pk_mul_f32 v[98:99], v[70:71], v[70:71]
	v_cmp_gt_i32_e64 s[0:1], 12, v21
	v_fmac_f32_e32 v53, v25, v23
	v_cos_f32_e32 v23, v66
	v_sin_f32_e32 v95, v66
	v_mul_lo_u32 v66, v21, s26
	v_add_f32_e32 v21, v96, v98
	v_mov_b32_e32 v110, v68
	v_mov_b32_e32 v111, v58
	v_add_f32_e32 v21, v21, v97
	v_lshlrev_b32_e32 v69, 16, v55
	v_and_b32_e32 v59, 0xffff0000, v55
	v_pk_mul_f32 v[110:111], v[110:111], v[110:111]
	v_add_f32_e32 v21, v21, v99
	v_mov_b32_e32 v112, v69
	v_mov_b32_e32 v113, v59
	v_add_f32_e32 v21, v21, v110
	v_pk_mul_f32 v[112:113], v[112:113], v[112:113]
	v_add_f32_e32 v21, v21, v111
	v_mov_b32_e32 v74, v56
	v_mov_b32_e32 v75, v54
	v_add_f32_e32 v21, v21, v112
	v_lshlrev_b32_e32 v57, 16, v67
	v_and_b32_e32 v55, 0xffff0000, v67
	v_pk_mul_f32 v[74:75], v[74:75], v[74:75]
	v_add_f32_e32 v21, v21, v113
	v_mov_b32_e32 v76, v57
	v_mov_b32_e32 v77, v55
	v_add_f32_e32 v21, v21, v74
	v_pk_mul_f32 v[76:77], v[76:77], v[76:77]
	v_add_f32_e32 v21, v21, v75
	v_add_f32_e32 v21, v21, v76
	v_add_f32_e32 v21, v21, v77
	v_cndmask_b32_e64 v93, 1.0, v23, s[4:5]
	ds_swizzle_b32 v23, v21 offset:swizzle(SWAP,1)
	v_cndmask_b32_e64 v52, 1.0, v225, s[0:1]
	v_cndmask_b32_e64 v79, v1, v7, s[0:1]
	v_cndmask_b32_e64 v78, v0, v12, s[0:1]
	v_cndmask_b32_e64 v87, v61, v13, s[0:1]
	s_waitcnt lgkmcnt(0)
	v_add_f32_e32 v21, v21, v23
	ds_swizzle_b32 v23, v21 offset:swizzle(SWAP,2)
	v_cndmask_b32_e64 v86, v62, v6, s[0:1]
	v_cndmask_b32_e64 v101, v3, v9, s[0:1]
	v_cndmask_b32_e64 v100, v8, v20, s[0:1]
	v_cndmask_b32_e64 v107, v63, v15, s[0:1]
	s_waitcnt lgkmcnt(0)
	v_add_f32_e32 v21, v21, v23
	ds_swizzle_b32 v23, v21 offset:swizzle(SWAP,4)
	v_cndmask_b32_e64 v106, v2, v14, s[0:1]
	v_cndmask_b32_e64 v77, v5, v11, s[0:1]
	v_cndmask_b32_e64 v76, v4, v16, s[0:1]
	v_cndmask_b32_e64 v111, v65, v17, s[0:1]
	s_waitcnt lgkmcnt(0)
	v_add_f32_e32 v21, v21, v23
	v_cndmask_b32_e64 v110, v10, v22, s[0:1]
	v_fmamk_f32 v21, v21, 0x3c2aaaab, v224
	s_mov_b32 s0, 0x800000
	v_mul_f32_e32 v23, 0x4b800000, v21
	v_cmp_gt_f32_e64 s[0:1], s0, v21
	v_cos_f32_e32 v64, v53
	v_cndmask_b32_e64 v103, 1.0, v102, s[4:5]
	v_cndmask_b32_e64 v21, v21, v23, s[0:1]
	v_rsq_f32_e32 v21, v21
	v_cndmask_b32_e64 v102, 1.0, v64, s[4:5]
	v_sin_f32_e32 v53, v53
	v_cndmask_b32_e64 v105, 0, v104, s[4:5]
	v_mul_f32_e32 v23, 0x45800000, v21
	v_cndmask_b32_e64 v64, v21, v23, s[0:1]
	v_pk_mul_f32 v[72:73], v[64:65], v[72:73] op_sel_hi:[0,1]
	v_pk_mul_f32 v[72:73], v[72:73], v[100:101]
	ds_swizzle_b32 v21, v73 offset:swizzle(SWAP,1)
	ds_swizzle_b32 v23, v72 offset:swizzle(SWAP,1)
	v_pk_mul_f32 v[70:71], v[64:65], v[70:71] op_sel_hi:[0,1]
	v_pk_mul_f32 v[70:71], v[70:71], v[106:107]
	v_cndmask_b32_e64 v104, 0, v53, s[4:5]
	s_waitcnt lgkmcnt(1)
	v_cndmask_b32_e64 v101, v21, -v21, vcc
	ds_swizzle_b32 v21, v71 offset:swizzle(SWAP,1)
	ds_swizzle_b32 v53, v70 offset:swizzle(SWAP,1)
	s_waitcnt lgkmcnt(2)
	v_cndmask_b32_e64 v100, v23, -v23, vcc
	v_pk_mul_f32 v[68:69], v[64:65], v[68:69] op_sel_hi:[0,1]
	v_pk_mul_f32 v[100:101], v[100:101], v[104:105]
	v_pk_mul_f32 v[68:69], v[68:69], v[76:77]
	v_pk_fma_f32 v[72:73], v[72:73], v[102:103], v[100:101]
	s_waitcnt lgkmcnt(1)
	v_cndmask_b32_e64 v101, v21, -v21, vcc
	ds_swizzle_b32 v21, v69 offset:swizzle(SWAP,1)
	v_cndmask_b32_e64 v75, 0, v115, s[4:5]
	v_cndmask_b32_e64 v74, 0, v114, s[4:5]
	s_waitcnt lgkmcnt(1)
	v_cndmask_b32_e64 v100, v53, -v53, vcc
	ds_swizzle_b32 v23, v68 offset:swizzle(SWAP,1)
	v_pk_mul_f32 v[58:59], v[64:65], v[58:59] op_sel_hi:[0,1]
	v_cndmask_b32_e64 v109, 1.0, v108, s[4:5]
	v_cndmask_b32_e64 v108, 1.0, v85, s[4:5]
	v_pk_mul_f32 v[74:75], v[100:101], v[74:75]
	v_pk_mul_f32 v[58:59], v[58:59], v[110:111]
	v_pk_fma_f32 v[70:71], v[70:71], v[108:109], v[74:75]
	s_waitcnt lgkmcnt(1)
	v_cndmask_b32_e64 v75, v21, -v21, vcc
	ds_swizzle_b32 v21, v59 offset:swizzle(SWAP,1)
	v_pk_mul_f32 v[72:73], v[52:53], v[72:73] op_sel_hi:[0,1]
	v_pk_mul_f32 v[70:71], v[52:53], v[70:71] op_sel_hi:[0,1]
	ds_swizzle_b32 v53, v58 offset:swizzle(SWAP,1)
	v_cndmask_b32_e64 v99, 0, v121, s[4:5]
	v_cndmask_b32_e64 v98, 0, v117, s[4:5]
	s_waitcnt lgkmcnt(2)
	v_cndmask_b32_e64 v74, v23, -v23, vcc
	v_pk_mul_f32 v[56:57], v[64:65], v[56:57] op_sel_hi:[0,1]
	v_cndmask_b32_e64 v97, 1.0, v120, s[4:5]
	v_cndmask_b32_e64 v96, 1.0, v116, s[4:5]
	v_pk_mul_f32 v[74:75], v[74:75], v[98:99]
	v_pk_mul_f32 v[56:57], v[56:57], v[78:79]
	v_pk_fma_f32 v[68:69], v[68:69], v[96:97], v[74:75]
	s_waitcnt lgkmcnt(1)
	v_cndmask_b32_e64 v75, v21, -v21, vcc
	ds_swizzle_b32 v21, v57 offset:swizzle(SWAP,1)
	v_cndmask_b32_e64 v115, 0, v123, s[4:5]
	v_cndmask_b32_e64 v114, 0, v119, s[4:5]
	s_waitcnt lgkmcnt(1)
	v_cndmask_b32_e64 v74, v53, -v53, vcc
	v_cndmask_b32_e64 v113, 1.0, v122, s[4:5]
	v_cndmask_b32_e64 v112, 1.0, v118, s[4:5]
	v_pk_mul_f32 v[74:75], v[74:75], v[114:115]
	ds_swizzle_b32 v23, v56 offset:swizzle(SWAP,1)
	v_pk_mul_f32 v[54:55], v[64:65], v[54:55] op_sel_hi:[0,1]
	v_pk_fma_f32 v[58:59], v[58:59], v[112:113], v[74:75]
	v_pk_mul_f32 v[54:55], v[54:55], v[86:87]
	v_pk_mul_f32 v[68:69], v[52:53], v[68:69] op_sel_hi:[0,1]
	v_pk_mul_f32 v[58:59], v[52:53], v[58:59] op_sel_hi:[0,1]
	ds_swizzle_b32 v53, v54 offset:swizzle(SWAP,1)
	s_waitcnt lgkmcnt(2)
	v_cndmask_b32_e64 v75, v21, -v21, vcc
	ds_swizzle_b32 v21, v55 offset:swizzle(SWAP,1)
	v_cndmask_b32_e64 v91, 0, v91, s[4:5]
	v_cndmask_b32_e64 v90, 0, v90, s[4:5]
	s_waitcnt lgkmcnt(2)
	v_cndmask_b32_e64 v74, v23, -v23, vcc
	v_cndmask_b32_e64 v89, 1.0, v89, s[4:5]
	v_cndmask_b32_e64 v88, 1.0, v88, s[4:5]
	v_pk_mul_f32 v[74:75], v[74:75], v[90:91]
	v_cndmask_b32_e64 v95, 0, v95, s[4:5]
	v_cndmask_b32_e64 v94, 0, v94, s[4:5]
	v_pk_fma_f32 v[56:57], v[56:57], v[88:89], v[74:75]
	s_waitcnt lgkmcnt(0)
	v_cndmask_b32_e64 v75, v21, -v21, vcc
	v_cndmask_b32_e64 v74, v53, -v53, vcc
	v_cndmask_b32_e64 v92, 1.0, v92, s[4:5]
	v_pk_mul_f32 v[74:75], v[74:75], v[94:95]
	v_pk_mul_f32 v[56:57], v[52:53], v[56:57] op_sel_hi:[0,1]
	v_pk_fma_f32 v[54:55], v[54:55], v[92:93], v[74:75]
	v_pk_mul_f32 v[74:75], v[52:53], v[54:55] op_sel_hi:[0,1]
	v_cvt_pk_bf16_f32 v52, v72, v70
	v_cvt_pk_bf16_f32 v53, v73, v71
	v_cvt_pk_bf16_f32 v54, v68, v58
	v_cvt_pk_bf16_f32 v55, v69, v59
	v_cvt_pk_bf16_f32 v56, v56, v74
	v_cvt_pk_bf16_f32 v57, v57, v75
	s_mulk_i32 s18, 0x4200
	s_mov_b32 s0, 0xffff0000
	s_add_u32 s18, s14, s18
	s_addc_u32 s19, s15, 0
	v_ashrrev_i32_e32 v67, 31, v66
	v_lshl_add_u64 v[66:67], v[66:67], 1, s[18:19]
	v_lshl_add_u64 v[66:67], v[66:67], 0, v[204:205]
	global_store_dwordx4 v[66:67], v[52:55], off
	global_store_dwordx2 v[66:67], v[56:57], off offset:16
.LBB0_324:
	s_cmp_gt_i32 s25, 0xbfff
	s_cbranch_scc1 .LBB0_319
	s_mul_hi_i32 s0, s25, 0x55555556
	s_lshr_b32 s1, s0, 31
	s_add_i32 s0, s0, s1
	s_lshr_b32 s1, s0, 7
	s_and_b32 s1, s1, 56
	s_cmpk_lt_u32 s0, 0x2000
	s_cselect_b32 s18, 4, 0
	s_or_b32 s1, s18, s1
	s_bfe_u32 s18, s0, 0x20008
	s_or_b32 s1, s1, s18
	s_mul_i32 s18, s0, 3
	s_lshl_b32 s1, s1, 8
	s_sub_i32 s18, s25, s18
	s_and_b32 s0, s0, 0xff
	v_lshl_or_b32 v21, s18, 3, v80
	s_or_b32 s18, s1, s0
	s_and_b32 s0, s18, s20
	v_cvt_f32_u32_e32 v23, s0
	s_waitcnt vmcnt(2)
	v_lshlrev_b32_e32 v67, 16, v49
	v_and_b32_e32 v59, 0xffff0000, v49
	v_lshlrev_b32_e32 v57, 16, v51
	v_mul_f32_e32 v54, v26, v23
	v_fract_f32_e32 v54, v54
	v_fmac_f32_e32 v54, v27, v23
	v_cos_f32_e32 v85, v54
	v_sin_f32_e32 v108, v54
	v_mul_f32_e32 v54, v28, v23
	v_fract_f32_e32 v54, v54
	v_fmac_f32_e32 v54, v29, v23
	v_cos_f32_e32 v96, v54
	v_sin_f32_e32 v98, v54
	v_mul_f32_e32 v54, v30, v23
	v_fract_f32_e32 v54, v54
	v_fmac_f32_e32 v54, v31, v23
	v_cos_f32_e32 v102, v54
	v_sin_f32_e32 v109, v54
	v_mul_f32_e32 v54, v32, v23
	v_fract_f32_e32 v54, v54
	v_fmac_f32_e32 v54, v33, v23
	v_cos_f32_e32 v110, v54
	v_sin_f32_e32 v111, v54
	v_mul_f32_e32 v54, v34, v23
	v_fract_f32_e32 v54, v54
	v_fmac_f32_e32 v54, v35, v23
	v_and_b32_e32 v53, 0xffff0000, v51
	v_lshlrev_b32_e32 v51, 16, v19
	v_and_b32_e32 v49, 0xffff0000, v19
	v_mul_f32_e32 v19, v24, v23
	v_cos_f32_e32 v112, v54
	v_sin_f32_e32 v113, v54
	v_mul_f32_e32 v54, v36, v23
	v_fract_f32_e32 v19, v19
	v_fract_f32_e32 v54, v54
	v_fmac_f32_e32 v19, v25, v23
	v_fmac_f32_e32 v54, v37, v23
	v_cos_f32_e32 v64, v19
	v_sin_f32_e32 v19, v19
	v_cos_f32_e32 v114, v54
	v_sin_f32_e32 v115, v54
	v_mul_f32_e32 v54, v38, v23
	v_fract_f32_e32 v54, v54
	v_lshlrev_b32_e32 v66, 16, v48
	v_and_b32_e32 v58, 0xffff0000, v48
	v_fmac_f32_e32 v54, v39, v23
	v_cos_f32_e32 v116, v54
	v_sin_f32_e32 v117, v54
	v_mul_f32_e32 v54, v40, v23
	v_pk_mul_f32 v[90:91], v[66:67], v[66:67]
	v_pk_mul_f32 v[92:93], v[58:59], v[58:59]
	v_lshlrev_b32_e32 v56, 16, v50
	v_and_b32_e32 v52, 0xffff0000, v50
	v_fract_f32_e32 v54, v54
	v_cndmask_b32_e64 v99, 0, v98, s[4:5]
	v_cndmask_b32_e64 v98, 0, v19, s[4:5]
	v_add_f32_e32 v19, v90, v92
	v_fmac_f32_e32 v54, v41, v23
	v_mov_b32_e32 v104, v56
	v_mov_b32_e32 v105, v52
	v_add_f32_e32 v19, v19, v91
	v_cos_f32_e32 v76, v54
	v_sin_f32_e32 v78, v54
	v_mul_f32_e32 v54, v42, v23
	v_pk_mul_f32 v[104:105], v[104:105], v[104:105]
	v_add_f32_e32 v19, v19, v93
	v_fract_f32_e32 v54, v54
	v_mov_b32_e32 v106, v57
	v_mov_b32_e32 v107, v53
	v_add_f32_e32 v19, v19, v104
	v_lshlrev_b32_e32 v50, 16, v18
	v_and_b32_e32 v48, 0xffff0000, v18
	v_fmac_f32_e32 v54, v43, v23
	v_pk_mul_f32 v[106:107], v[106:107], v[106:107]
	v_add_f32_e32 v19, v19, v105
	v_cos_f32_e32 v86, v54
	v_sin_f32_e32 v88, v54
	v_mul_f32_e32 v54, v44, v23
	v_mov_b32_e32 v68, v50
	v_mov_b32_e32 v69, v48
	v_add_f32_e32 v19, v19, v106
	v_fract_f32_e32 v54, v54
	v_pk_mul_f32 v[68:69], v[68:69], v[68:69]
	v_add_f32_e32 v19, v19, v107
	v_fmac_f32_e32 v54, v45, v23
	v_mov_b32_e32 v70, v51
	v_mov_b32_e32 v71, v49
	v_add_f32_e32 v19, v19, v68
	v_cos_f32_e32 v77, v54
	v_sin_f32_e32 v79, v54
	v_mul_f32_e32 v54, v46, v23
	v_pk_mul_f32 v[70:71], v[70:71], v[70:71]
	v_add_f32_e32 v19, v19, v69
	v_fract_f32_e32 v54, v54
	v_add_f32_e32 v19, v19, v70
	v_fmac_f32_e32 v54, v47, v23
	s_movk_i32 s25, 0x60
	v_add_f32_e32 v19, v19, v71
	v_cmp_gt_i32_e64 s[0:1], 12, v21
	v_cos_f32_e32 v23, v54
	v_sin_f32_e32 v89, v54
	v_mul_lo_u32 v54, v21, s25
	ds_swizzle_b32 v21, v19 offset:swizzle(SWAP,1)
	v_cndmask_b32_e64 v18, 1.0, v225, s[0:1]
	v_cndmask_b32_e64 v73, v1, v7, s[0:1]
	v_cndmask_b32_e64 v72, v0, v12, s[0:1]
	v_cndmask_b32_e64 v75, v61, v13, s[0:1]
	s_waitcnt lgkmcnt(0)
	v_add_f32_e32 v19, v19, v21
	ds_swizzle_b32 v21, v19 offset:swizzle(SWAP,2)
	v_cndmask_b32_e64 v74, v62, v6, s[0:1]
	v_cndmask_b32_e64 v95, v3, v9, s[0:1]
	v_cndmask_b32_e64 v94, v8, v20, s[0:1]
	v_cndmask_b32_e64 v101, v63, v15, s[0:1]
	s_waitcnt lgkmcnt(0)
	v_add_f32_e32 v19, v19, v21
	ds_swizzle_b32 v21, v19 offset:swizzle(SWAP,4)
	v_cndmask_b32_e64 v100, v2, v14, s[0:1]
	v_cndmask_b32_e64 v71, v5, v11, s[0:1]
	v_cndmask_b32_e64 v70, v4, v16, s[0:1]
	v_cndmask_b32_e64 v105, v65, v17, s[0:1]
	s_waitcnt lgkmcnt(0)
	v_add_f32_e32 v19, v19, v21
	v_cndmask_b32_e64 v104, v10, v22, s[0:1]
	v_fmamk_f32 v19, v19, 0x3c2aaaab, v224
	s_mov_b32 s0, 0x800000
	v_mul_f32_e32 v21, 0x4b800000, v19
	v_cmp_gt_f32_e64 s[0:1], s0, v19
	v_cndmask_b32_e64 v97, 1.0, v96, s[4:5]
	v_cndmask_b32_e64 v96, 1.0, v64, s[4:5]
	v_cndmask_b32_e64 v19, v19, v21, s[0:1]
	v_rsq_f32_e32 v19, v19
	v_cndmask_b32_e64 v87, 1.0, v23, s[4:5]
	v_cndmask_b32_e64 v69, 0, v109, s[4:5]
	v_cndmask_b32_e64 v68, 0, v108, s[4:5]
	v_mul_f32_e32 v21, 0x45800000, v19
	v_cndmask_b32_e64 v64, v19, v21, s[0:1]
	v_pk_mul_f32 v[66:67], v[64:65], v[66:67] op_sel_hi:[0,1]
	v_pk_mul_f32 v[66:67], v[66:67], v[94:95]
	ds_swizzle_b32 v19, v67 offset:swizzle(SWAP,1)
	ds_swizzle_b32 v21, v66 offset:swizzle(SWAP,1)
	v_pk_mul_f32 v[58:59], v[64:65], v[58:59] op_sel_hi:[0,1]
	v_pk_mul_f32 v[58:59], v[58:59], v[100:101]
	ds_swizzle_b32 v23, v58 offset:swizzle(SWAP,1)
	s_waitcnt lgkmcnt(2)
	v_cndmask_b32_e64 v95, v19, -v19, vcc
	ds_swizzle_b32 v19, v59 offset:swizzle(SWAP,1)
	s_waitcnt lgkmcnt(2)
	v_cndmask_b32_e64 v94, v21, -v21, vcc
	v_pk_mul_f32 v[94:95], v[94:95], v[98:99]
	v_cndmask_b32_e64 v103, 1.0, v102, s[4:5]
	v_pk_fma_f32 v[66:67], v[66:67], v[96:97], v[94:95]
	s_waitcnt lgkmcnt(0)
	v_cndmask_b32_e64 v95, v19, -v19, vcc
	v_cndmask_b32_e64 v94, v23, -v23, vcc
	v_cndmask_b32_e64 v102, 1.0, v85, s[4:5]
	v_pk_mul_f32 v[68:69], v[94:95], v[68:69]
	v_pk_mul_f32 v[56:57], v[64:65], v[56:57] op_sel_hi:[0,1]
	v_pk_fma_f32 v[58:59], v[58:59], v[102:103], v[68:69]
	v_pk_mul_f32 v[56:57], v[56:57], v[70:71]
	v_pk_mul_f32 v[66:67], v[18:19], v[66:67] op_sel_hi:[0,1]
	v_pk_mul_f32 v[58:59], v[18:19], v[58:59] op_sel_hi:[0,1]
	ds_swizzle_b32 v19, v57 offset:swizzle(SWAP,1)
	ds_swizzle_b32 v21, v56 offset:swizzle(SWAP,1)
	v_pk_mul_f32 v[52:53], v[64:65], v[52:53] op_sel_hi:[0,1]
	v_pk_mul_f32 v[52:53], v[52:53], v[104:105]
	ds_swizzle_b32 v23, v52 offset:swizzle(SWAP,1)
	s_waitcnt lgkmcnt(2)
	v_cndmask_b32_e64 v69, v19, -v19, vcc
	ds_swizzle_b32 v19, v53 offset:swizzle(SWAP,1)
	v_cndmask_b32_e64 v93, 0, v115, s[4:5]
	v_cndmask_b32_e64 v92, 0, v111, s[4:5]
	s_waitcnt lgkmcnt(2)
	v_cndmask_b32_e64 v68, v21, -v21, vcc
	v_cndmask_b32_e64 v91, 1.0, v114, s[4:5]
	v_cndmask_b32_e64 v90, 1.0, v110, s[4:5]
	v_pk_mul_f32 v[68:69], v[68:69], v[92:93]
	v_cndmask_b32_e64 v109, 0, v117, s[4:5]
	v_cndmask_b32_e64 v108, 0, v113, s[4:5]
	v_pk_fma_f32 v[56:57], v[56:57], v[90:91], v[68:69]
	s_waitcnt lgkmcnt(0)
	v_cndmask_b32_e64 v69, v19, -v19, vcc
	v_cndmask_b32_e64 v68, v23, -v23, vcc
	v_cndmask_b32_e64 v107, 1.0, v116, s[4:5]
	v_cndmask_b32_e64 v106, 1.0, v112, s[4:5]
	v_pk_mul_f32 v[68:69], v[68:69], v[108:109]
	v_pk_mul_f32 v[50:51], v[64:65], v[50:51] op_sel_hi:[0,1]
	v_pk_fma_f32 v[52:53], v[52:53], v[106:107], v[68:69]
	v_pk_mul_f32 v[50:51], v[50:51], v[72:73]
	v_pk_mul_f32 v[56:57], v[18:19], v[56:57] op_sel_hi:[0,1]
	v_pk_mul_f32 v[52:53], v[18:19], v[52:53] op_sel_hi:[0,1]
	ds_swizzle_b32 v19, v51 offset:swizzle(SWAP,1)
	ds_swizzle_b32 v21, v50 offset:swizzle(SWAP,1)
	v_pk_mul_f32 v[48:49], v[64:65], v[48:49] op_sel_hi:[0,1]
	v_pk_mul_f32 v[48:49], v[48:49], v[74:75]
	ds_swizzle_b32 v23, v48 offset:swizzle(SWAP,1)
	s_waitcnt lgkmcnt(2)
	v_cndmask_b32_e64 v69, v19, -v19, vcc
	ds_swizzle_b32 v19, v49 offset:swizzle(SWAP,1)
	v_cndmask_b32_e64 v79, 0, v79, s[4:5]
	v_cndmask_b32_e64 v78, 0, v78, s[4:5]
	s_waitcnt lgkmcnt(2)
	v_cndmask_b32_e64 v68, v21, -v21, vcc
	v_cndmask_b32_e64 v77, 1.0, v77, s[4:5]
	v_cndmask_b32_e64 v76, 1.0, v76, s[4:5]
	v_pk_mul_f32 v[68:69], v[68:69], v[78:79]
	v_cndmask_b32_e64 v89, 0, v89, s[4:5]
	v_pk_fma_f32 v[50:51], v[50:51], v[76:77], v[68:69]
	v_cndmask_b32_e64 v88, 0, v88, s[4:5]
	s_waitcnt lgkmcnt(0)
	v_pk_mul_f32 v[68:69], v[18:19], v[50:51] op_sel_hi:[0,1]
	v_cndmask_b32_e64 v51, v19, -v19, vcc
	v_cndmask_b32_e64 v50, v23, -v23, vcc
	v_cndmask_b32_e64 v86, 1.0, v86, s[4:5]
	v_pk_mul_f32 v[50:51], v[50:51], v[88:89]
	v_pk_fma_f32 v[48:49], v[48:49], v[86:87], v[50:51]
	v_pk_mul_f32 v[18:19], v[18:19], v[48:49] op_sel_hi:[0,1]
	v_cvt_pk_bf16_f32 v48, v66, v58
	v_cvt_pk_bf16_f32 v49, v67, v59
	v_cvt_pk_bf16_f32 v50, v56, v52
	v_cvt_pk_bf16_f32 v51, v57, v53
	v_cvt_pk_bf16_f32 v18, v68, v18
	v_cvt_pk_bf16_f32 v19, v69, v19
	s_mulk_i32 s18, 0x4200
	s_add_u32 s18, s14, s18
	s_mov_b32 s0, 0xffff0000
	s_addc_u32 s19, s15, 0
	v_ashrrev_i32_e32 v55, 31, v54
	v_lshl_add_u64 v[54:55], v[54:55], 1, s[18:19]
	v_lshl_add_u64 v[54:55], v[54:55], 0, v[204:205]
	global_store_dwordx4 v[54:55], v[48:51], off
	global_store_dwordx2 v[54:55], v[18:19], off offset:16
	s_branch .LBB0_319

.LBB0_348:
	s_or_b64 exec, exec, s[20:21]
	s_waitcnt vmcnt(0)
	v_lshlrev_b32_e32 v44, 16, v28
	v_and_b32_e32 v28, 0xffff0000, v28
	v_lshlrev_b32_e32 v45, 16, v29
	v_and_b32_e32 v29, 0xffff0000, v29
	v_mov_b32_e32 v46, v44
	v_mov_b32_e32 v47, v28
	v_pk_mul_f32 v[46:47], v[46:47], v[46:47]
	v_mov_b32_e32 v66, v45
	v_mov_b32_e32 v67, v29
	v_pk_mul_f32 v[66:67], v[66:67], v[66:67]
	v_lshlrev_b32_e32 v68, 16, v30
	v_and_b32_e32 v78, 0xffff0000, v30
	v_add_f32_e32 v46, v46, v47
	v_lshlrev_b32_e32 v69, 16, v31
	v_and_b32_e32 v79, 0xffff0000, v31
	v_mov_b32_e32 v30, v68
	v_mov_b32_e32 v31, v78
	v_add_f32_e32 v46, v46, v66
	v_pk_mul_f32 v[30:31], v[30:31], v[30:31]
	v_add_f32_e32 v46, v46, v67
	v_mov_b32_e32 v70, v69
	v_mov_b32_e32 v71, v79
	v_add_f32_e32 v30, v46, v30
	v_pk_mul_f32 v[70:71], v[70:71], v[70:71]
	v_add_f32_e32 v30, v30, v31
	v_add_f32_e32 v30, v30, v70
	v_add_f32_e32 v30, v30, v71
	ds_swizzle_b32 v31, v30 offset:swizzle(SWAP,1)
	s_mov_b32 s8, 0x800000
	s_waitcnt lgkmcnt(0)
	v_add_f32_e32 v30, v30, v31
	ds_swizzle_b32 v31, v30 offset:swizzle(SWAP,2)
	s_waitcnt lgkmcnt(0)
	v_add_f32_e32 v30, v30, v31
	ds_swizzle_b32 v31, v30 offset:swizzle(SWAP,4)
	s_waitcnt lgkmcnt(0)
	v_add_f32_e32 v30, v30, v31
	v_fmamk_f32 v30, v30, 0x3c800000, v224
	v_mul_f32_e32 v31, 0x4b800000, v30
	v_cmp_gt_f32_e64 s[8:9], s8, v30
	s_nop 1
	v_cndmask_b32_e64 v30, v30, v31, s[8:9]
	v_rsq_f32_e32 v30, v30
	s_nop 0
	v_mul_f32_e32 v31, 0x45800000, v30
	v_cndmask_b32_e64 v46, v30, v31, s[8:9]
	v_pk_mul_f32 v[30:31], v[46:47], v[44:45] op_sel_hi:[0,1]
	v_pk_mul_f32 v[28:29], v[46:47], v[28:29] op_sel_hi:[0,1]
	v_pk_mul_f32 v[44:45], v[46:47], v[68:69] op_sel_hi:[0,1]
	v_pk_mul_f32 v[46:47], v[46:47], v[78:79] op_sel_hi:[0,1]
	v_pk_mul_f32 v[30:31], v[30:31], v[34:35]
	v_pk_mul_f32 v[28:29], v[28:29], v[36:37]
	v_pk_mul_f32 v[44:45], v[44:45], v[38:39]
	v_pk_mul_f32 v[46:47], v[46:47], v[40:41]
	ds_swizzle_b32 v72, v30 offset:swizzle(SWAP,1)
	ds_swizzle_b32 v73, v30 offset:swizzle(SWAP,2)
	ds_swizzle_b32 v70, v28 offset:swizzle(SWAP,1)
	ds_swizzle_b32 v71, v28 offset:swizzle(SWAP,2)
	ds_swizzle_b32 v76, v31 offset:swizzle(SWAP,1)
	ds_swizzle_b32 v77, v31 offset:swizzle(SWAP,2)
	ds_swizzle_b32 v74, v29 offset:swizzle(SWAP,1)
	ds_swizzle_b32 v75, v29 offset:swizzle(SWAP,2)
	ds_swizzle_b32 v66, v44 offset:swizzle(SWAP,1)
	ds_swizzle_b32 v67, v44 offset:swizzle(SWAP,2)
	ds_swizzle_b32 v78, v46 offset:swizzle(SWAP,1)
	ds_swizzle_b32 v79, v46 offset:swizzle(SWAP,2)
	ds_swizzle_b32 v68, v45 offset:swizzle(SWAP,1)
	ds_swizzle_b32 v69, v45 offset:swizzle(SWAP,2)
	ds_swizzle_b32 v83, v47 offset:swizzle(SWAP,1)
	ds_swizzle_b32 v84, v47 offset:swizzle(SWAP,2)
	s_and_saveexec_b64 s[8:9], s[18:19]
	s_cbranch_execz .LBB0_350
	s_ashr_i32 s20, s3, 1
	s_cmpk_lt_u32 s20, 0x2000
	s_cselect_b32 s21, 4, 0
	s_lshr_b32 s33, s20, 7
	s_and_b32 s33, s33, 56
	s_or_b32 s21, s21, s33
	s_bfe_u32 s33, s20, 0x20008
	s_or_b32 s21, s21, s33
	s_lshl_b32 s21, s21, 8
	s_and_b32 s33, s20, 0xff
	s_or_b32 s21, s21, s33
	s_and_b32 s33, s21, s23
	s_lshr_b32 s34, s33, 6
	s_and_b32 s20, s20, 63
	v_mov_b32_e32 v85, s20
	v_mov_b32_e32 v86, s34
	v_cndmask_b32_e64 v85, v85, v86, s[0:1]
	v_mov_b32_e32 v86, s33
	v_cndmask_b32_e64 v85, v86, v85, s[10:11]
	v_cvt_f32_u32_e32 v85, v85
	s_waitcnt lgkmcnt(8)
	v_cndmask_b32_e64 v74, v74, v75, s[10:11]
	v_cndmask_b32_e64 v75, v70, v71, s[10:11]
	s_waitcnt lgkmcnt(6)
	v_cndmask_b32_e64 v94, v66, v67, s[10:11]
	v_mul_f32_e32 v70, v56, v85
	v_fract_f32_e32 v70, v70
	v_fmac_f32_e32 v70, v57, v85
	v_cos_f32_e32 v88, v70
	v_sin_f32_e32 v89, v70
	v_mul_f32_e32 v70, v58, v85
	v_fract_f32_e32 v70, v70
	v_fmac_f32_e32 v70, v59, v85
	v_cos_f32_e32 v90, v70
	v_sin_f32_e32 v91, v70
	v_mul_f32_e32 v70, v60, v85
	v_mul_f32_e32 v66, v62, v85
	v_mul_f32_e32 v86, v50, v85
	v_fract_f32_e32 v70, v70
	v_fract_f32_e32 v66, v66
	v_fract_f32_e32 v86, v86
	v_fmac_f32_e32 v70, v61, v85
	v_fmac_f32_e32 v66, v63, v85
	v_fmac_f32_e32 v86, v51, v85
	v_cos_f32_e32 v92, v70
	s_waitcnt lgkmcnt(2)
	v_cndmask_b32_e64 v93, v68, v69, s[10:11]
	v_sin_f32_e32 v95, v70
	v_cos_f32_e32 v68, v66
	v_sin_f32_e32 v70, v66
	v_mul_f32_e32 v66, v64, v85
	v_cndmask_b32_e64 v78, v78, v79, s[10:11]
	v_sin_f32_e32 v79, v86
	v_fract_f32_e32 v66, v66
	v_cos_f32_e32 v87, v86
	s_waitcnt lgkmcnt(0)
	v_cndmask_b32_e64 v83, v83, v84, s[10:11]
	v_mul_f32_e32 v84, v52, v85
	v_cndmask_b32_e64 v76, v76, v77, s[10:11]
	v_mul_f32_e32 v77, v54, v85
	v_fmac_f32_e32 v66, v65, v85
	v_fract_f32_e32 v84, v84
	v_fract_f32_e32 v77, v77
	v_sin_f32_e32 v96, v66
	v_fmac_f32_e32 v84, v53, v85
	v_fmac_f32_e32 v77, v55, v85
	v_cos_f32_e32 v85, v66
	v_cndmask_b32_e64 v72, v72, v73, s[10:11]
	v_sin_f32_e32 v73, v84
	v_cndmask_b32_e64 v66, 1.0, v68, s[4:5]
	v_cndmask_b32_e64 v68, v78, -v78, s[6:7]
	v_cndmask_b32_e64 v69, v83, -v83, s[6:7]
	v_cndmask_b32_e64 v71, 0, v79, s[4:5]
	v_cndmask_b32_e64 v70, 0, v70, s[4:5]
	v_cos_f32_e32 v86, v84
	v_cndmask_b32_e64 v67, 1.0, v87, s[4:5]
	v_pk_mul_f32 v[68:69], v[68:69], v[70:71]
	v_cos_f32_e32 v84, v77
	v_sin_f32_e32 v77, v77
	v_pk_fma_f32 v[46:47], v[46:47], v[66:67], v[68:69]
	v_cndmask_b32_e64 v68, v94, -v94, s[6:7]
	v_cndmask_b32_e64 v69, v93, -v93, s[6:7]
	v_cndmask_b32_e64 v71, 0, v96, s[4:5]
	v_cndmask_b32_e64 v70, 0, v95, s[4:5]
	v_cndmask_b32_e64 v67, 1.0, v85, s[4:5]
	v_cndmask_b32_e64 v66, 1.0, v92, s[4:5]
	v_pk_mul_f32 v[68:69], v[68:69], v[70:71]
	v_cndmask_b32_e64 v71, 0, v89, s[4:5]
	v_pk_fma_f32 v[44:45], v[44:45], v[66:67], v[68:69]
	v_cndmask_b32_e64 v68, v72, -v72, s[6:7]
	v_cndmask_b32_e64 v69, v76, -v76, s[6:7]
	v_cndmask_b32_e64 v70, 0, v73, s[4:5]
	v_cndmask_b32_e64 v67, 1.0, v88, s[4:5]
	v_cndmask_b32_e64 v66, 1.0, v86, s[4:5]
	v_pk_mul_f32 v[68:69], v[68:69], v[70:71]
	v_cndmask_b32_e64 v71, 0, v91, s[4:5]
	v_pk_fma_f32 v[30:31], v[30:31], v[66:67], v[68:69]
	v_cndmask_b32_e64 v68, v75, -v75, s[6:7]
	v_cndmask_b32_e64 v69, v74, -v74, s[6:7]
	v_cndmask_b32_e64 v70, 0, v77, s[4:5]
	v_cndmask_b32_e64 v67, 1.0, v90, s[4:5]
	v_cndmask_b32_e64 v66, 1.0, v84, s[4:5]
	v_pk_mul_f32 v[68:69], v[68:69], v[70:71]
	s_mov_b32 s20, 0xffff0000
	v_pk_fma_f32 v[28:29], v[28:29], v[66:67], v[68:69]
	v_cvt_pk_bf16_f32 v28, v30, v28
	v_cvt_pk_bf16_f32 v29, v31, v29
	v_cvt_pk_bf16_f32 v30, v44, v46
	v_cvt_pk_bf16_f32 v31, v45, v47
	s_mul_i32 s86, s21, 0x4200
	v_lshl_add_u64 v[44:45], v[42:43], 0, s[86:87]
	global_store_dwordx4 v[44:45], v[28:31], off
.LBB0_350:
	s_or_b64 exec, exec, s[8:9]
	s_cmpk_gt_i32 s31, 0x7fff
	s_cbranch_scc1 .LBB0_354
	v_lshlrev_b32_e32 v28, 16, v24
	v_and_b32_e32 v24, 0xffff0000, v24
	v_lshlrev_b32_e32 v29, 16, v25
	v_and_b32_e32 v25, 0xffff0000, v25
	v_mov_b32_e32 v30, v28
	v_mov_b32_e32 v31, v24
	v_pk_mul_f32 v[30:31], v[30:31], v[30:31]
	v_mov_b32_e32 v44, v29
	v_mov_b32_e32 v45, v25
	v_pk_mul_f32 v[44:45], v[44:45], v[44:45]
	v_lshlrev_b32_e32 v46, 16, v26
	s_waitcnt lgkmcnt(9)
	v_and_b32_e32 v74, 0xffff0000, v26
	v_add_f32_e32 v30, v30, v31
	v_lshlrev_b32_e32 v47, 16, v27
	s_waitcnt lgkmcnt(8)
	v_and_b32_e32 v75, 0xffff0000, v27
	v_mov_b32_e32 v26, v46
	v_mov_b32_e32 v27, v74
	v_add_f32_e32 v30, v30, v44
	v_pk_mul_f32 v[26:27], v[26:27], v[26:27]
	v_add_f32_e32 v30, v30, v45
	s_waitcnt lgkmcnt(7)
	v_mov_b32_e32 v66, v47
	s_waitcnt lgkmcnt(6)
	v_mov_b32_e32 v67, v75
	v_add_f32_e32 v26, v30, v26
	v_pk_mul_f32 v[66:67], v[66:67], v[66:67]
	v_add_f32_e32 v26, v26, v27
	v_add_f32_e32 v26, v26, v66
	v_add_f32_e32 v26, v26, v67
	ds_swizzle_b32 v27, v26 offset:swizzle(SWAP,1)
	s_mov_b32 s8, 0x800000
	s_waitcnt lgkmcnt(0)
	v_add_f32_e32 v26, v26, v27
	ds_swizzle_b32 v27, v26 offset:swizzle(SWAP,2)
	s_waitcnt lgkmcnt(0)
	v_add_f32_e32 v26, v26, v27
	ds_swizzle_b32 v27, v26 offset:swizzle(SWAP,4)
	s_waitcnt lgkmcnt(0)
	v_add_f32_e32 v26, v26, v27
	v_fmamk_f32 v26, v26, 0x3c800000, v224
	v_mul_f32_e32 v27, 0x4b800000, v26
	v_cmp_gt_f32_e64 s[8:9], s8, v26
	s_nop 1
	v_cndmask_b32_e64 v26, v26, v27, s[8:9]
	v_rsq_f32_e32 v26, v26
	s_nop 0
	v_mul_f32_e32 v27, 0x45800000, v26
	v_cndmask_b32_e64 v30, v26, v27, s[8:9]
	v_pk_mul_f32 v[26:27], v[30:31], v[28:29] op_sel_hi:[0,1]
	v_pk_mul_f32 v[24:25], v[30:31], v[24:25] op_sel_hi:[0,1]
	v_pk_mul_f32 v[28:29], v[30:31], v[46:47] op_sel_hi:[0,1]
	v_pk_mul_f32 v[30:31], v[30:31], v[74:75] op_sel_hi:[0,1]
	v_pk_mul_f32 v[26:27], v[26:27], v[34:35]
	v_pk_mul_f32 v[24:25], v[24:25], v[36:37]
	v_pk_mul_f32 v[28:29], v[28:29], v[38:39]
	v_pk_mul_f32 v[30:31], v[30:31], v[40:41]
	ds_swizzle_b32 v68, v26 offset:swizzle(SWAP,1)
	ds_swizzle_b32 v69, v26 offset:swizzle(SWAP,2)
	ds_swizzle_b32 v66, v24 offset:swizzle(SWAP,1)
	ds_swizzle_b32 v67, v24 offset:swizzle(SWAP,2)
	ds_swizzle_b32 v72, v27 offset:swizzle(SWAP,1)
	ds_swizzle_b32 v73, v27 offset:swizzle(SWAP,2)
	ds_swizzle_b32 v70, v25 offset:swizzle(SWAP,1)
	ds_swizzle_b32 v71, v25 offset:swizzle(SWAP,2)
	ds_swizzle_b32 v44, v28 offset:swizzle(SWAP,1)
	ds_swizzle_b32 v45, v28 offset:swizzle(SWAP,2)
	ds_swizzle_b32 v74, v30 offset:swizzle(SWAP,1)
	ds_swizzle_b32 v75, v30 offset:swizzle(SWAP,2)
	ds_swizzle_b32 v46, v29 offset:swizzle(SWAP,1)
	ds_swizzle_b32 v47, v29 offset:swizzle(SWAP,2)
	ds_swizzle_b32 v76, v31 offset:swizzle(SWAP,1)
	ds_swizzle_b32 v77, v31 offset:swizzle(SWAP,2)
	s_and_saveexec_b64 s[8:9], s[18:19]
	s_cbranch_execz .LBB0_353
	s_ashr_i32 s20, s31, 1
	s_cmpk_lt_u32 s20, 0x2000
	s_cselect_b32 s21, 4, 0
	s_lshr_b32 s31, s20, 7
	s_and_b32 s31, s31, 56
	s_or_b32 s21, s21, s31
	s_bfe_u32 s31, s20, 0x20008
	s_or_b32 s21, s21, s31
	s_lshl_b32 s21, s21, 8
	s_and_b32 s31, s20, 0xff
	s_or_b32 s21, s21, s31
	s_and_b32 s31, s21, s23
	s_lshr_b32 s33, s31, 6
	s_and_b32 s20, s20, 63
	v_mov_b32_e32 v78, s20
	v_mov_b32_e32 v79, s33
	v_cndmask_b32_e64 v78, v78, v79, s[0:1]
	v_mov_b32_e32 v79, s31
	v_cndmask_b32_e64 v78, v79, v78, s[10:11]
	v_cvt_f32_u32_e32 v78, v78
	s_waitcnt lgkmcnt(8)
	v_cndmask_b32_e64 v70, v70, v71, s[10:11]
	v_cndmask_b32_e64 v71, v66, v67, s[10:11]
	s_waitcnt lgkmcnt(6)
	v_cndmask_b32_e64 v90, v44, v45, s[10:11]
	v_mul_f32_e32 v66, v56, v78
	v_fract_f32_e32 v66, v66
	v_fmac_f32_e32 v66, v57, v78
	v_cos_f32_e32 v84, v66
	v_sin_f32_e32 v85, v66
	v_mul_f32_e32 v66, v58, v78
	v_fract_f32_e32 v66, v66
	v_fmac_f32_e32 v66, v59, v78
	v_cos_f32_e32 v86, v66
	v_sin_f32_e32 v87, v66
	v_mul_f32_e32 v66, v60, v78
	v_mul_f32_e32 v44, v62, v78
	v_mul_f32_e32 v79, v50, v78
	v_fract_f32_e32 v66, v66
	v_fract_f32_e32 v44, v44
	v_fract_f32_e32 v79, v79
	v_fmac_f32_e32 v66, v61, v78
	v_fmac_f32_e32 v44, v63, v78
	v_fmac_f32_e32 v79, v51, v78
	v_cos_f32_e32 v88, v66
	s_waitcnt lgkmcnt(2)
	v_cndmask_b32_e64 v89, v46, v47, s[10:11]
	v_sin_f32_e32 v91, v66
	v_cos_f32_e32 v46, v44
	v_sin_f32_e32 v66, v44
	v_mul_f32_e32 v44, v64, v78
	v_cndmask_b32_e64 v74, v74, v75, s[10:11]
	v_sin_f32_e32 v75, v79
	v_fract_f32_e32 v44, v44
	v_cos_f32_e32 v83, v79
	s_waitcnt lgkmcnt(0)
	v_cndmask_b32_e64 v76, v76, v77, s[10:11]
	v_mul_f32_e32 v77, v52, v78
	v_cndmask_b32_e64 v72, v72, v73, s[10:11]
	v_mul_f32_e32 v73, v54, v78
	v_fmac_f32_e32 v44, v65, v78
	v_fract_f32_e32 v77, v77
	v_fract_f32_e32 v73, v73
	v_sin_f32_e32 v92, v44
	v_fmac_f32_e32 v77, v53, v78
	v_fmac_f32_e32 v73, v55, v78
	v_cos_f32_e32 v78, v44
	v_cndmask_b32_e64 v68, v68, v69, s[10:11]
	v_sin_f32_e32 v69, v77
	v_cndmask_b32_e64 v44, 1.0, v46, s[4:5]
	v_cndmask_b32_e64 v46, v74, -v74, s[6:7]
	v_cndmask_b32_e64 v47, v76, -v76, s[6:7]
	v_cndmask_b32_e64 v67, 0, v75, s[4:5]
	v_cndmask_b32_e64 v66, 0, v66, s[4:5]
	v_cos_f32_e32 v79, v77
	v_cndmask_b32_e64 v45, 1.0, v83, s[4:5]
	v_pk_mul_f32 v[46:47], v[46:47], v[66:67]
	v_cos_f32_e32 v77, v73
	v_sin_f32_e32 v73, v73
	v_pk_fma_f32 v[30:31], v[30:31], v[44:45], v[46:47]
	v_cndmask_b32_e64 v46, v90, -v90, s[6:7]
	v_cndmask_b32_e64 v47, v89, -v89, s[6:7]
	v_cndmask_b32_e64 v67, 0, v92, s[4:5]
	v_cndmask_b32_e64 v66, 0, v91, s[4:5]
	v_cndmask_b32_e64 v45, 1.0, v78, s[4:5]
	v_cndmask_b32_e64 v44, 1.0, v88, s[4:5]
	v_pk_mul_f32 v[46:47], v[46:47], v[66:67]
	v_cndmask_b32_e64 v67, 0, v85, s[4:5]
	v_pk_fma_f32 v[28:29], v[28:29], v[44:45], v[46:47]
	v_cndmask_b32_e64 v46, v68, -v68, s[6:7]
	v_cndmask_b32_e64 v47, v72, -v72, s[6:7]
	v_cndmask_b32_e64 v66, 0, v69, s[4:5]
	v_cndmask_b32_e64 v45, 1.0, v84, s[4:5]
	v_cndmask_b32_e64 v44, 1.0, v79, s[4:5]
	v_pk_mul_f32 v[46:47], v[46:47], v[66:67]
	v_cndmask_b32_e64 v67, 0, v87, s[4:5]
	v_pk_fma_f32 v[26:27], v[26:27], v[44:45], v[46:47]
	v_cndmask_b32_e64 v46, v71, -v71, s[6:7]
	v_cndmask_b32_e64 v47, v70, -v70, s[6:7]
	v_cndmask_b32_e64 v66, 0, v73, s[4:5]
	v_cndmask_b32_e64 v45, 1.0, v86, s[4:5]
	v_cndmask_b32_e64 v44, 1.0, v77, s[4:5]
	v_pk_mul_f32 v[46:47], v[46:47], v[66:67]
	s_mov_b32 s20, 0xffff0000
	v_pk_fma_f32 v[24:25], v[24:25], v[44:45], v[46:47]
	v_cvt_pk_bf16_f32 v24, v26, v24
	v_cvt_pk_bf16_f32 v25, v27, v25
	v_cvt_pk_bf16_f32 v26, v28, v30
	v_cvt_pk_bf16_f32 v27, v29, v31
	s_mul_i32 s86, s21, 0x4200
	v_lshl_add_u64 v[28:29], v[42:43], 0, s[86:87]
	global_store_dwordx4 v[28:29], v[24:27], off

.LBB0_354:
	s_cmpk_gt_i32 s30, 0x7fff
	s_cbranch_scc1 .LBB0_358
	v_lshlrev_b32_e32 v24, 16, v20
	v_and_b32_e32 v20, 0xffff0000, v20
	v_lshlrev_b32_e32 v25, 16, v21
	v_and_b32_e32 v21, 0xffff0000, v21
	v_mov_b32_e32 v26, v24
	v_mov_b32_e32 v27, v20
	v_pk_mul_f32 v[26:27], v[26:27], v[26:27]
	v_mov_b32_e32 v28, v25
	v_mov_b32_e32 v29, v21
	v_pk_mul_f32 v[28:29], v[28:29], v[28:29]
	v_lshlrev_b32_e32 v30, 16, v22
	s_waitcnt lgkmcnt(9)
	v_and_b32_e32 v70, 0xffff0000, v22
	v_add_f32_e32 v26, v26, v27
	v_lshlrev_b32_e32 v31, 16, v23
	s_waitcnt lgkmcnt(8)
	v_and_b32_e32 v71, 0xffff0000, v23
	v_mov_b32_e32 v22, v30
	v_mov_b32_e32 v23, v70
	v_add_f32_e32 v26, v26, v28
	v_pk_mul_f32 v[22:23], v[22:23], v[22:23]
	v_add_f32_e32 v26, v26, v29
	s_waitcnt lgkmcnt(7)
	v_mov_b32_e32 v44, v31
	s_waitcnt lgkmcnt(6)
	v_mov_b32_e32 v45, v71
	v_add_f32_e32 v22, v26, v22
	v_pk_mul_f32 v[44:45], v[44:45], v[44:45]
	v_add_f32_e32 v22, v22, v23
	v_add_f32_e32 v22, v22, v44
	v_add_f32_e32 v22, v22, v45
	ds_swizzle_b32 v23, v22 offset:swizzle(SWAP,1)
	s_mov_b32 s8, 0x800000
	s_waitcnt lgkmcnt(0)
	v_add_f32_e32 v22, v22, v23
	ds_swizzle_b32 v23, v22 offset:swizzle(SWAP,2)
	s_waitcnt lgkmcnt(0)
	v_add_f32_e32 v22, v22, v23
	ds_swizzle_b32 v23, v22 offset:swizzle(SWAP,4)
	s_waitcnt lgkmcnt(0)
	v_add_f32_e32 v22, v22, v23
	v_fmamk_f32 v22, v22, 0x3c800000, v224
	v_mul_f32_e32 v23, 0x4b800000, v22
	v_cmp_gt_f32_e64 s[8:9], s8, v22
	s_nop 1
	v_cndmask_b32_e64 v22, v22, v23, s[8:9]
	v_rsq_f32_e32 v22, v22
	s_nop 0
	v_mul_f32_e32 v23, 0x45800000, v22
	v_cndmask_b32_e64 v26, v22, v23, s[8:9]
	v_pk_mul_f32 v[22:23], v[26:27], v[24:25] op_sel_hi:[0,1]
	v_pk_mul_f32 v[20:21], v[26:27], v[20:21] op_sel_hi:[0,1]
	v_pk_mul_f32 v[24:25], v[26:27], v[30:31] op_sel_hi:[0,1]
	v_pk_mul_f32 v[26:27], v[26:27], v[70:71] op_sel_hi:[0,1]
	v_pk_mul_f32 v[22:23], v[22:23], v[34:35]
	v_pk_mul_f32 v[20:21], v[20:21], v[36:37]
	v_pk_mul_f32 v[24:25], v[24:25], v[38:39]
	v_pk_mul_f32 v[26:27], v[26:27], v[40:41]
	ds_swizzle_b32 v46, v22 offset:swizzle(SWAP,1)
	ds_swizzle_b32 v47, v22 offset:swizzle(SWAP,2)
	ds_swizzle_b32 v44, v20 offset:swizzle(SWAP,1)
	ds_swizzle_b32 v45, v20 offset:swizzle(SWAP,2)
	ds_swizzle_b32 v68, v23 offset:swizzle(SWAP,1)
	ds_swizzle_b32 v69, v23 offset:swizzle(SWAP,2)
	ds_swizzle_b32 v66, v21 offset:swizzle(SWAP,1)
	ds_swizzle_b32 v67, v21 offset:swizzle(SWAP,2)
	ds_swizzle_b32 v28, v24 offset:swizzle(SWAP,1)
	ds_swizzle_b32 v29, v24 offset:swizzle(SWAP,2)
	ds_swizzle_b32 v70, v26 offset:swizzle(SWAP,1)
	ds_swizzle_b32 v71, v26 offset:swizzle(SWAP,2)
	ds_swizzle_b32 v30, v25 offset:swizzle(SWAP,1)
	ds_swizzle_b32 v31, v25 offset:swizzle(SWAP,2)
	ds_swizzle_b32 v72, v27 offset:swizzle(SWAP,1)
	ds_swizzle_b32 v73, v27 offset:swizzle(SWAP,2)
	s_and_saveexec_b64 s[8:9], s[18:19]
	s_cbranch_execz .LBB0_357
	s_ashr_i32 s20, s30, 1
	s_cmpk_lt_u32 s20, 0x2000
	s_cselect_b32 s21, 4, 0
	s_lshr_b32 s30, s20, 7
	s_and_b32 s30, s30, 56
	s_or_b32 s21, s21, s30
	s_bfe_u32 s30, s20, 0x20008
	s_or_b32 s21, s21, s30
	s_lshl_b32 s21, s21, 8
	s_and_b32 s30, s20, 0xff
	s_or_b32 s21, s21, s30
	s_and_b32 s30, s21, s23
	s_lshr_b32 s31, s30, 6
	s_and_b32 s20, s20, 63
	v_mov_b32_e32 v74, s20
	v_mov_b32_e32 v75, s31
	v_cndmask_b32_e64 v74, v74, v75, s[0:1]
	v_mov_b32_e32 v75, s30
	v_cndmask_b32_e64 v74, v75, v74, s[10:11]
	v_cvt_f32_u32_e32 v74, v74
	s_waitcnt lgkmcnt(8)
	v_cndmask_b32_e64 v66, v66, v67, s[10:11]
	v_cndmask_b32_e64 v67, v44, v45, s[10:11]
	s_waitcnt lgkmcnt(6)
	v_cndmask_b32_e64 v86, v28, v29, s[10:11]
	v_mul_f32_e32 v44, v56, v74
	v_fract_f32_e32 v44, v44
	v_fmac_f32_e32 v44, v57, v74
	v_cos_f32_e32 v77, v44
	v_sin_f32_e32 v78, v44
	v_mul_f32_e32 v44, v58, v74
	v_fract_f32_e32 v44, v44
	v_fmac_f32_e32 v44, v59, v74
	v_cos_f32_e32 v79, v44
	v_sin_f32_e32 v83, v44
	v_mul_f32_e32 v44, v60, v74
	v_mul_f32_e32 v28, v62, v74
	v_mul_f32_e32 v75, v50, v74
	v_fract_f32_e32 v44, v44
	v_fract_f32_e32 v28, v28
	v_fract_f32_e32 v75, v75
	v_fmac_f32_e32 v44, v61, v74
	v_fmac_f32_e32 v28, v63, v74
	v_fmac_f32_e32 v75, v51, v74
	v_cos_f32_e32 v84, v44
	s_waitcnt lgkmcnt(2)
	v_cndmask_b32_e64 v85, v30, v31, s[10:11]
	v_sin_f32_e32 v87, v44
	v_cos_f32_e32 v30, v28
	v_sin_f32_e32 v44, v28
	v_mul_f32_e32 v28, v64, v74
	v_cndmask_b32_e64 v70, v70, v71, s[10:11]
	v_sin_f32_e32 v71, v75
	v_fract_f32_e32 v28, v28
	v_cos_f32_e32 v76, v75
	s_waitcnt lgkmcnt(0)
	v_cndmask_b32_e64 v72, v72, v73, s[10:11]
	v_mul_f32_e32 v73, v52, v74
	v_cndmask_b32_e64 v68, v68, v69, s[10:11]
	v_mul_f32_e32 v69, v54, v74
	v_fmac_f32_e32 v28, v65, v74
	v_fract_f32_e32 v73, v73
	v_fract_f32_e32 v69, v69
	v_sin_f32_e32 v88, v28
	v_fmac_f32_e32 v73, v53, v74
	v_fmac_f32_e32 v69, v55, v74
	v_cos_f32_e32 v74, v28
	v_cndmask_b32_e64 v46, v46, v47, s[10:11]
	v_sin_f32_e32 v47, v73
	v_cndmask_b32_e64 v28, 1.0, v30, s[4:5]
	v_cndmask_b32_e64 v30, v70, -v70, s[6:7]
	v_cndmask_b32_e64 v31, v72, -v72, s[6:7]
	v_cndmask_b32_e64 v45, 0, v71, s[4:5]
	v_cndmask_b32_e64 v44, 0, v44, s[4:5]
	v_cos_f32_e32 v75, v73
	v_cndmask_b32_e64 v29, 1.0, v76, s[4:5]
	v_pk_mul_f32 v[30:31], v[30:31], v[44:45]
	v_cos_f32_e32 v73, v69
	v_sin_f32_e32 v69, v69
	v_pk_fma_f32 v[26:27], v[26:27], v[28:29], v[30:31]
	v_cndmask_b32_e64 v30, v86, -v86, s[6:7]
	v_cndmask_b32_e64 v31, v85, -v85, s[6:7]
	v_cndmask_b32_e64 v45, 0, v88, s[4:5]
	v_cndmask_b32_e64 v44, 0, v87, s[4:5]
	v_cndmask_b32_e64 v29, 1.0, v74, s[4:5]
	v_cndmask_b32_e64 v28, 1.0, v84, s[4:5]
	v_pk_mul_f32 v[30:31], v[30:31], v[44:45]
	v_cndmask_b32_e64 v45, 0, v78, s[4:5]
	v_pk_fma_f32 v[24:25], v[24:25], v[28:29], v[30:31]
	v_cndmask_b32_e64 v30, v46, -v46, s[6:7]
	v_cndmask_b32_e64 v31, v68, -v68, s[6:7]
	v_cndmask_b32_e64 v44, 0, v47, s[4:5]
	v_cndmask_b32_e64 v29, 1.0, v77, s[4:5]
	v_cndmask_b32_e64 v28, 1.0, v75, s[4:5]
	v_pk_mul_f32 v[30:31], v[30:31], v[44:45]
	v_cndmask_b32_e64 v45, 0, v83, s[4:5]
	v_pk_fma_f32 v[22:23], v[22:23], v[28:29], v[30:31]
	v_cndmask_b32_e64 v30, v67, -v67, s[6:7]
	v_cndmask_b32_e64 v31, v66, -v66, s[6:7]
	v_cndmask_b32_e64 v44, 0, v69, s[4:5]
	v_cndmask_b32_e64 v29, 1.0, v79, s[4:5]
	v_cndmask_b32_e64 v28, 1.0, v73, s[4:5]
	v_pk_mul_f32 v[30:31], v[30:31], v[44:45]
	s_mov_b32 s20, 0xffff0000
	v_pk_fma_f32 v[20:21], v[20:21], v[28:29], v[30:31]
	v_cvt_pk_bf16_f32 v20, v22, v20
	v_cvt_pk_bf16_f32 v21, v23, v21
	v_cvt_pk_bf16_f32 v22, v24, v26
	v_cvt_pk_bf16_f32 v23, v25, v27
	s_mul_i32 s86, s21, 0x4200
	v_lshl_add_u64 v[24:25], v[42:43], 0, s[86:87]
	global_store_dwordx4 v[24:25], v[20:23], off

.LBB0_358:
	s_cmpk_gt_i32 s29, 0x7fff
	s_cbranch_scc1 .LBB0_362
	v_lshlrev_b32_e32 v20, 16, v16
	v_and_b32_e32 v16, 0xffff0000, v16
	v_lshlrev_b32_e32 v21, 16, v17
	v_and_b32_e32 v17, 0xffff0000, v17
	v_mov_b32_e32 v22, v20
	v_mov_b32_e32 v23, v16
	v_pk_mul_f32 v[22:23], v[22:23], v[22:23]
	v_mov_b32_e32 v24, v21
	v_mov_b32_e32 v25, v17
	v_pk_mul_f32 v[24:25], v[24:25], v[24:25]
	v_lshlrev_b32_e32 v26, 16, v18
	s_waitcnt lgkmcnt(7)
	v_and_b32_e32 v66, 0xffff0000, v18
	v_add_f32_e32 v22, v22, v23
	v_lshlrev_b32_e32 v27, 16, v19
	s_waitcnt lgkmcnt(6)
	v_and_b32_e32 v67, 0xffff0000, v19
	v_mov_b32_e32 v18, v26
	v_mov_b32_e32 v19, v66
	v_add_f32_e32 v22, v22, v24
	v_pk_mul_f32 v[18:19], v[18:19], v[18:19]
	v_add_f32_e32 v22, v22, v25
	v_mov_b32_e32 v28, v27
	v_mov_b32_e32 v29, v67
	v_add_f32_e32 v18, v22, v18
	v_pk_mul_f32 v[28:29], v[28:29], v[28:29]
	v_add_f32_e32 v18, v18, v19
	v_add_f32_e32 v18, v18, v28
	v_add_f32_e32 v18, v18, v29
	ds_swizzle_b32 v19, v18 offset:swizzle(SWAP,1)
	s_mov_b32 s8, 0x800000
	s_waitcnt lgkmcnt(0)
	v_add_f32_e32 v18, v18, v19
	ds_swizzle_b32 v19, v18 offset:swizzle(SWAP,2)
	s_waitcnt lgkmcnt(0)
	v_add_f32_e32 v18, v18, v19
	ds_swizzle_b32 v19, v18 offset:swizzle(SWAP,4)
	s_waitcnt lgkmcnt(0)
	v_add_f32_e32 v18, v18, v19
	v_fmamk_f32 v18, v18, 0x3c800000, v224
	v_mul_f32_e32 v19, 0x4b800000, v18
	v_cmp_gt_f32_e64 s[8:9], s8, v18
	s_nop 1
	v_cndmask_b32_e64 v18, v18, v19, s[8:9]
	v_rsq_f32_e32 v18, v18
	s_nop 0
	v_mul_f32_e32 v19, 0x45800000, v18
	v_cndmask_b32_e64 v22, v18, v19, s[8:9]
	v_pk_mul_f32 v[18:19], v[22:23], v[20:21] op_sel_hi:[0,1]
	v_pk_mul_f32 v[16:17], v[22:23], v[16:17] op_sel_hi:[0,1]
	v_pk_mul_f32 v[20:21], v[22:23], v[26:27] op_sel_hi:[0,1]
	v_pk_mul_f32 v[22:23], v[22:23], v[66:67] op_sel_hi:[0,1]
	v_pk_mul_f32 v[18:19], v[18:19], v[34:35]
	v_pk_mul_f32 v[16:17], v[16:17], v[36:37]
	v_pk_mul_f32 v[20:21], v[20:21], v[38:39]
	v_pk_mul_f32 v[22:23], v[22:23], v[40:41]
	ds_swizzle_b32 v30, v18 offset:swizzle(SWAP,1)
	ds_swizzle_b32 v31, v18 offset:swizzle(SWAP,2)
	ds_swizzle_b32 v28, v16 offset:swizzle(SWAP,1)
	ds_swizzle_b32 v29, v16 offset:swizzle(SWAP,2)
	ds_swizzle_b32 v46, v19 offset:swizzle(SWAP,1)
	ds_swizzle_b32 v47, v19 offset:swizzle(SWAP,2)
	ds_swizzle_b32 v44, v17 offset:swizzle(SWAP,1)
	ds_swizzle_b32 v45, v17 offset:swizzle(SWAP,2)
	ds_swizzle_b32 v24, v20 offset:swizzle(SWAP,1)
	ds_swizzle_b32 v25, v20 offset:swizzle(SWAP,2)
	ds_swizzle_b32 v66, v22 offset:swizzle(SWAP,1)
	ds_swizzle_b32 v67, v22 offset:swizzle(SWAP,2)
	ds_swizzle_b32 v26, v21 offset:swizzle(SWAP,1)
	ds_swizzle_b32 v27, v21 offset:swizzle(SWAP,2)
	ds_swizzle_b32 v68, v23 offset:swizzle(SWAP,1)
	ds_swizzle_b32 v69, v23 offset:swizzle(SWAP,2)
	s_and_saveexec_b64 s[8:9], s[18:19]
	s_cbranch_execz .LBB0_361
	s_ashr_i32 s20, s29, 1
	s_cmpk_lt_u32 s20, 0x2000
	s_cselect_b32 s21, 4, 0
	s_lshr_b32 s29, s20, 7
	s_and_b32 s29, s29, 56
	s_or_b32 s21, s21, s29
	s_bfe_u32 s29, s20, 0x20008
	s_or_b32 s21, s21, s29
	s_lshl_b32 s21, s21, 8
	s_and_b32 s29, s20, 0xff
	s_or_b32 s21, s21, s29
	s_and_b32 s29, s21, s23
	s_lshr_b32 s30, s29, 6
	s_and_b32 s20, s20, 63
	v_mov_b32_e32 v70, s20
	v_mov_b32_e32 v71, s30
	v_cndmask_b32_e64 v70, v70, v71, s[0:1]
	v_mov_b32_e32 v71, s29
	v_cndmask_b32_e64 v70, v71, v70, s[10:11]
	v_cvt_f32_u32_e32 v70, v70
	s_waitcnt lgkmcnt(8)
	v_cndmask_b32_e64 v44, v44, v45, s[10:11]
	v_cndmask_b32_e64 v45, v28, v29, s[10:11]
	s_waitcnt lgkmcnt(6)
	v_cndmask_b32_e64 v79, v24, v25, s[10:11]
	v_mul_f32_e32 v28, v56, v70
	v_fract_f32_e32 v28, v28
	v_fmac_f32_e32 v28, v57, v70
	v_cos_f32_e32 v73, v28
	v_sin_f32_e32 v74, v28
	v_mul_f32_e32 v28, v58, v70
	v_fract_f32_e32 v28, v28
	v_fmac_f32_e32 v28, v59, v70
	v_cos_f32_e32 v75, v28
	v_sin_f32_e32 v76, v28
	v_mul_f32_e32 v28, v60, v70
	v_mul_f32_e32 v24, v62, v70
	v_mul_f32_e32 v71, v50, v70
	v_fract_f32_e32 v28, v28
	v_fract_f32_e32 v24, v24
	v_fract_f32_e32 v71, v71
	v_fmac_f32_e32 v28, v61, v70
	v_fmac_f32_e32 v24, v63, v70
	v_fmac_f32_e32 v71, v51, v70
	v_cos_f32_e32 v77, v28
	s_waitcnt lgkmcnt(2)
	v_cndmask_b32_e64 v78, v26, v27, s[10:11]
	v_sin_f32_e32 v83, v28
	v_cos_f32_e32 v26, v24
	v_sin_f32_e32 v28, v24
	v_mul_f32_e32 v24, v64, v70
	v_cndmask_b32_e64 v66, v66, v67, s[10:11]
	v_sin_f32_e32 v67, v71
	v_fract_f32_e32 v24, v24
	v_cos_f32_e32 v72, v71
	s_waitcnt lgkmcnt(0)
	v_cndmask_b32_e64 v68, v68, v69, s[10:11]
	v_mul_f32_e32 v69, v52, v70
	v_cndmask_b32_e64 v46, v46, v47, s[10:11]
	v_mul_f32_e32 v47, v54, v70
	v_fmac_f32_e32 v24, v65, v70
	v_fract_f32_e32 v69, v69
	v_fract_f32_e32 v47, v47
	v_sin_f32_e32 v84, v24
	v_fmac_f32_e32 v69, v53, v70
	v_fmac_f32_e32 v47, v55, v70
	v_cos_f32_e32 v70, v24
	v_cndmask_b32_e64 v30, v30, v31, s[10:11]
	v_sin_f32_e32 v31, v69
	v_cndmask_b32_e64 v24, 1.0, v26, s[4:5]
	v_cndmask_b32_e64 v26, v66, -v66, s[6:7]
	v_cndmask_b32_e64 v27, v68, -v68, s[6:7]
	v_cndmask_b32_e64 v29, 0, v67, s[4:5]
	v_cndmask_b32_e64 v28, 0, v28, s[4:5]
	v_cos_f32_e32 v71, v69
	v_cndmask_b32_e64 v25, 1.0, v72, s[4:5]
	v_pk_mul_f32 v[26:27], v[26:27], v[28:29]
	v_cos_f32_e32 v69, v47
	v_sin_f32_e32 v47, v47
	v_pk_fma_f32 v[22:23], v[22:23], v[24:25], v[26:27]
	v_cndmask_b32_e64 v26, v79, -v79, s[6:7]
	v_cndmask_b32_e64 v27, v78, -v78, s[6:7]
	v_cndmask_b32_e64 v29, 0, v84, s[4:5]
	v_cndmask_b32_e64 v28, 0, v83, s[4:5]
	v_cndmask_b32_e64 v25, 1.0, v70, s[4:5]
	v_cndmask_b32_e64 v24, 1.0, v77, s[4:5]
	v_pk_mul_f32 v[26:27], v[26:27], v[28:29]
	v_cndmask_b32_e64 v29, 0, v74, s[4:5]
	v_pk_fma_f32 v[20:21], v[20:21], v[24:25], v[26:27]
	v_cndmask_b32_e64 v26, v30, -v30, s[6:7]
	v_cndmask_b32_e64 v27, v46, -v46, s[6:7]
	v_cndmask_b32_e64 v28, 0, v31, s[4:5]
	v_cndmask_b32_e64 v25, 1.0, v73, s[4:5]
	v_cndmask_b32_e64 v24, 1.0, v71, s[4:5]
	v_pk_mul_f32 v[26:27], v[26:27], v[28:29]
	v_cndmask_b32_e64 v29, 0, v76, s[4:5]
	v_pk_fma_f32 v[18:19], v[18:19], v[24:25], v[26:27]
	v_cndmask_b32_e64 v26, v45, -v45, s[6:7]
	v_cndmask_b32_e64 v27, v44, -v44, s[6:7]
	v_cndmask_b32_e64 v28, 0, v47, s[4:5]
	v_cndmask_b32_e64 v25, 1.0, v75, s[4:5]
	v_cndmask_b32_e64 v24, 1.0, v69, s[4:5]
	v_pk_mul_f32 v[26:27], v[26:27], v[28:29]
	s_mov_b32 s20, 0xffff0000
	v_pk_fma_f32 v[16:17], v[16:17], v[24:25], v[26:27]
	v_cvt_pk_bf16_f32 v16, v18, v16
	v_cvt_pk_bf16_f32 v17, v19, v17
	v_cvt_pk_bf16_f32 v18, v20, v22
	v_cvt_pk_bf16_f32 v19, v21, v23
	s_mul_i32 s86, s21, 0x4200
	v_lshl_add_u64 v[20:21], v[42:43], 0, s[86:87]
	global_store_dwordx4 v[20:21], v[16:19], off

.LBB0_362:
	s_cmpk_gt_i32 s28, 0x7fff
	s_cbranch_scc1 .LBB0_366
	v_lshlrev_b32_e32 v16, 16, v12
	v_and_b32_e32 v12, 0xffff0000, v12
	v_lshlrev_b32_e32 v17, 16, v13
	v_and_b32_e32 v13, 0xffff0000, v13
	v_mov_b32_e32 v18, v16
	v_mov_b32_e32 v19, v12
	v_pk_mul_f32 v[18:19], v[18:19], v[18:19]
	v_mov_b32_e32 v20, v17
	v_mov_b32_e32 v21, v13
	v_pk_mul_f32 v[20:21], v[20:21], v[20:21]
	v_lshlrev_b32_e32 v22, 16, v14
	s_waitcnt lgkmcnt(7)
	v_and_b32_e32 v44, 0xffff0000, v14
	v_add_f32_e32 v18, v18, v19
	v_lshlrev_b32_e32 v23, 16, v15
	s_waitcnt lgkmcnt(6)
	v_and_b32_e32 v45, 0xffff0000, v15
	v_mov_b32_e32 v14, v22
	v_mov_b32_e32 v15, v44
	v_add_f32_e32 v18, v18, v20
	v_pk_mul_f32 v[14:15], v[14:15], v[14:15]
	v_add_f32_e32 v18, v18, v21
	v_mov_b32_e32 v24, v23
	v_mov_b32_e32 v25, v45
	v_add_f32_e32 v14, v18, v14
	v_pk_mul_f32 v[24:25], v[24:25], v[24:25]
	v_add_f32_e32 v14, v14, v15
	v_add_f32_e32 v14, v14, v24
	v_add_f32_e32 v14, v14, v25
	ds_swizzle_b32 v15, v14 offset:swizzle(SWAP,1)
	s_mov_b32 s8, 0x800000
	s_waitcnt lgkmcnt(0)
	v_add_f32_e32 v14, v14, v15
	ds_swizzle_b32 v15, v14 offset:swizzle(SWAP,2)
	s_waitcnt lgkmcnt(0)
	v_add_f32_e32 v14, v14, v15
	ds_swizzle_b32 v15, v14 offset:swizzle(SWAP,4)
	s_waitcnt lgkmcnt(0)
	v_add_f32_e32 v14, v14, v15
	v_fmamk_f32 v14, v14, 0x3c800000, v224
	v_mul_f32_e32 v15, 0x4b800000, v14
	v_cmp_gt_f32_e64 s[8:9], s8, v14
	s_nop 1
	v_cndmask_b32_e64 v14, v14, v15, s[8:9]
	v_rsq_f32_e32 v14, v14
	s_nop 0
	v_mul_f32_e32 v15, 0x45800000, v14
	v_cndmask_b32_e64 v18, v14, v15, s[8:9]
	v_pk_mul_f32 v[14:15], v[18:19], v[16:17] op_sel_hi:[0,1]
	v_pk_mul_f32 v[12:13], v[18:19], v[12:13] op_sel_hi:[0,1]
	v_pk_mul_f32 v[16:17], v[18:19], v[22:23] op_sel_hi:[0,1]
	v_pk_mul_f32 v[18:19], v[18:19], v[44:45] op_sel_hi:[0,1]
	v_pk_mul_f32 v[14:15], v[14:15], v[34:35]
	v_pk_mul_f32 v[12:13], v[12:13], v[36:37]
	v_pk_mul_f32 v[16:17], v[16:17], v[38:39]
	v_pk_mul_f32 v[18:19], v[18:19], v[40:41]
	ds_swizzle_b32 v26, v14 offset:swizzle(SWAP,1)
	ds_swizzle_b32 v27, v14 offset:swizzle(SWAP,2)
	ds_swizzle_b32 v24, v12 offset:swizzle(SWAP,1)
	ds_swizzle_b32 v25, v12 offset:swizzle(SWAP,2)
	ds_swizzle_b32 v30, v15 offset:swizzle(SWAP,1)
	ds_swizzle_b32 v31, v15 offset:swizzle(SWAP,2)
	ds_swizzle_b32 v28, v13 offset:swizzle(SWAP,1)
	ds_swizzle_b32 v29, v13 offset:swizzle(SWAP,2)
	ds_swizzle_b32 v20, v16 offset:swizzle(SWAP,1)
	ds_swizzle_b32 v21, v16 offset:swizzle(SWAP,2)
	ds_swizzle_b32 v44, v18 offset:swizzle(SWAP,1)
	ds_swizzle_b32 v45, v18 offset:swizzle(SWAP,2)
	ds_swizzle_b32 v22, v17 offset:swizzle(SWAP,1)
	ds_swizzle_b32 v23, v17 offset:swizzle(SWAP,2)
	ds_swizzle_b32 v46, v19 offset:swizzle(SWAP,1)
	ds_swizzle_b32 v47, v19 offset:swizzle(SWAP,2)
	s_and_saveexec_b64 s[8:9], s[18:19]
	s_cbranch_execz .LBB0_365
	s_ashr_i32 s20, s28, 1
	s_cmpk_lt_u32 s20, 0x2000
	s_cselect_b32 s21, 4, 0
	s_lshr_b32 s28, s20, 7
	s_and_b32 s28, s28, 56
	s_or_b32 s21, s21, s28
	s_bfe_u32 s28, s20, 0x20008
	s_or_b32 s21, s21, s28
	s_lshl_b32 s21, s21, 8
	s_and_b32 s28, s20, 0xff
	s_or_b32 s21, s21, s28
	s_and_b32 s28, s21, s23
	s_lshr_b32 s29, s28, 6
	s_and_b32 s20, s20, 63
	v_mov_b32_e32 v66, s20
	v_mov_b32_e32 v67, s29
	v_cndmask_b32_e64 v66, v66, v67, s[0:1]
	v_mov_b32_e32 v67, s28
	v_cndmask_b32_e64 v66, v67, v66, s[10:11]
	v_cvt_f32_u32_e32 v66, v66
	s_waitcnt lgkmcnt(8)
	v_cndmask_b32_e64 v28, v28, v29, s[10:11]
	v_cndmask_b32_e64 v29, v24, v25, s[10:11]
	s_waitcnt lgkmcnt(6)
	v_cndmask_b32_e64 v75, v20, v21, s[10:11]
	v_mul_f32_e32 v24, v56, v66
	v_fract_f32_e32 v24, v24
	v_fmac_f32_e32 v24, v57, v66
	v_cos_f32_e32 v69, v24
	v_sin_f32_e32 v70, v24
	v_mul_f32_e32 v24, v58, v66
	v_fract_f32_e32 v24, v24
	v_fmac_f32_e32 v24, v59, v66
	v_cos_f32_e32 v71, v24
	v_sin_f32_e32 v72, v24
	v_mul_f32_e32 v24, v60, v66
	v_mul_f32_e32 v20, v62, v66
	v_mul_f32_e32 v67, v50, v66
	v_fract_f32_e32 v24, v24
	v_fract_f32_e32 v20, v20
	v_fract_f32_e32 v67, v67
	v_fmac_f32_e32 v24, v61, v66
	v_fmac_f32_e32 v20, v63, v66
	v_fmac_f32_e32 v67, v51, v66
	v_cos_f32_e32 v73, v24
	s_waitcnt lgkmcnt(2)
	v_cndmask_b32_e64 v74, v22, v23, s[10:11]
	v_sin_f32_e32 v76, v24
	v_cos_f32_e32 v22, v20
	v_sin_f32_e32 v24, v20
	v_mul_f32_e32 v20, v64, v66
	v_cndmask_b32_e64 v44, v44, v45, s[10:11]
	v_sin_f32_e32 v45, v67
	v_fract_f32_e32 v20, v20
	v_cos_f32_e32 v68, v67
	s_waitcnt lgkmcnt(0)
	v_cndmask_b32_e64 v46, v46, v47, s[10:11]
	v_mul_f32_e32 v47, v52, v66
	v_cndmask_b32_e64 v30, v30, v31, s[10:11]
	v_mul_f32_e32 v31, v54, v66
	v_fmac_f32_e32 v20, v65, v66
	v_fract_f32_e32 v47, v47
	v_fract_f32_e32 v31, v31
	v_sin_f32_e32 v77, v20
	v_fmac_f32_e32 v47, v53, v66
	v_fmac_f32_e32 v31, v55, v66
	v_cos_f32_e32 v66, v20
	v_cndmask_b32_e64 v26, v26, v27, s[10:11]
	v_sin_f32_e32 v27, v47
	v_cndmask_b32_e64 v20, 1.0, v22, s[4:5]
	v_cndmask_b32_e64 v22, v44, -v44, s[6:7]
	v_cndmask_b32_e64 v23, v46, -v46, s[6:7]
	v_cndmask_b32_e64 v25, 0, v45, s[4:5]
	v_cndmask_b32_e64 v24, 0, v24, s[4:5]
	v_cos_f32_e32 v67, v47
	v_cndmask_b32_e64 v21, 1.0, v68, s[4:5]
	v_pk_mul_f32 v[22:23], v[22:23], v[24:25]
	v_cos_f32_e32 v47, v31
	v_sin_f32_e32 v31, v31
	v_pk_fma_f32 v[18:19], v[18:19], v[20:21], v[22:23]
	v_cndmask_b32_e64 v22, v75, -v75, s[6:7]
	v_cndmask_b32_e64 v23, v74, -v74, s[6:7]
	v_cndmask_b32_e64 v25, 0, v77, s[4:5]
	v_cndmask_b32_e64 v24, 0, v76, s[4:5]
	v_cndmask_b32_e64 v21, 1.0, v66, s[4:5]
	v_cndmask_b32_e64 v20, 1.0, v73, s[4:5]
	v_pk_mul_f32 v[22:23], v[22:23], v[24:25]
	v_cndmask_b32_e64 v25, 0, v70, s[4:5]
	v_pk_fma_f32 v[16:17], v[16:17], v[20:21], v[22:23]
	v_cndmask_b32_e64 v22, v26, -v26, s[6:7]
	v_cndmask_b32_e64 v23, v30, -v30, s[6:7]
	v_cndmask_b32_e64 v24, 0, v27, s[4:5]
	v_cndmask_b32_e64 v21, 1.0, v69, s[4:5]
	v_cndmask_b32_e64 v20, 1.0, v67, s[4:5]
	v_pk_mul_f32 v[22:23], v[22:23], v[24:25]
	v_cndmask_b32_e64 v25, 0, v72, s[4:5]
	v_pk_fma_f32 v[14:15], v[14:15], v[20:21], v[22:23]
	v_cndmask_b32_e64 v22, v29, -v29, s[6:7]
	v_cndmask_b32_e64 v23, v28, -v28, s[6:7]
	v_cndmask_b32_e64 v24, 0, v31, s[4:5]
	v_cndmask_b32_e64 v21, 1.0, v71, s[4:5]
	v_cndmask_b32_e64 v20, 1.0, v47, s[4:5]
	v_pk_mul_f32 v[22:23], v[22:23], v[24:25]
	s_mov_b32 s20, 0xffff0000
	v_pk_fma_f32 v[12:13], v[12:13], v[20:21], v[22:23]
	v_cvt_pk_bf16_f32 v12, v14, v12
	v_cvt_pk_bf16_f32 v13, v15, v13
	v_cvt_pk_bf16_f32 v14, v16, v18
	v_cvt_pk_bf16_f32 v15, v17, v19
	s_mul_i32 s86, s21, 0x4200
	v_lshl_add_u64 v[16:17], v[42:43], 0, s[86:87]
	global_store_dwordx4 v[16:17], v[12:15], off

.LBB0_366:
	s_cmpk_gt_i32 s27, 0x7fff
	s_cbranch_scc1 .LBB0_370
	v_lshlrev_b32_e32 v12, 16, v8
	v_and_b32_e32 v8, 0xffff0000, v8
	v_lshlrev_b32_e32 v13, 16, v9
	v_and_b32_e32 v9, 0xffff0000, v9
	v_mov_b32_e32 v14, v12
	v_mov_b32_e32 v15, v8
	v_pk_mul_f32 v[14:15], v[14:15], v[14:15]
	v_mov_b32_e32 v16, v13
	v_mov_b32_e32 v17, v9
	v_pk_mul_f32 v[16:17], v[16:17], v[16:17]
	v_lshlrev_b32_e32 v18, 16, v10
	s_waitcnt lgkmcnt(7)
	v_and_b32_e32 v28, 0xffff0000, v10
	v_add_f32_e32 v14, v14, v15
	v_lshlrev_b32_e32 v19, 16, v11
	s_waitcnt lgkmcnt(6)
	v_and_b32_e32 v29, 0xffff0000, v11
	v_mov_b32_e32 v10, v18
	v_mov_b32_e32 v11, v28
	v_add_f32_e32 v14, v14, v16
	v_pk_mul_f32 v[10:11], v[10:11], v[10:11]
	v_add_f32_e32 v14, v14, v17
	v_mov_b32_e32 v20, v19
	v_mov_b32_e32 v21, v29
	v_add_f32_e32 v10, v14, v10
	v_pk_mul_f32 v[20:21], v[20:21], v[20:21]
	v_add_f32_e32 v10, v10, v11
	v_add_f32_e32 v10, v10, v20
	v_add_f32_e32 v10, v10, v21
	ds_swizzle_b32 v11, v10 offset:swizzle(SWAP,1)
	s_mov_b32 s8, 0x800000
	s_waitcnt lgkmcnt(0)
	v_add_f32_e32 v10, v10, v11
	ds_swizzle_b32 v11, v10 offset:swizzle(SWAP,2)
	s_waitcnt lgkmcnt(0)
	v_add_f32_e32 v10, v10, v11
	ds_swizzle_b32 v11, v10 offset:swizzle(SWAP,4)
	s_waitcnt lgkmcnt(0)
	v_add_f32_e32 v10, v10, v11
	v_fmamk_f32 v10, v10, 0x3c800000, v224
	v_mul_f32_e32 v11, 0x4b800000, v10
	v_cmp_gt_f32_e64 s[8:9], s8, v10
	s_nop 1
	v_cndmask_b32_e64 v10, v10, v11, s[8:9]
	v_rsq_f32_e32 v10, v10
	s_nop 0
	v_mul_f32_e32 v11, 0x45800000, v10
	v_cndmask_b32_e64 v14, v10, v11, s[8:9]
	v_pk_mul_f32 v[10:11], v[14:15], v[12:13] op_sel_hi:[0,1]
	v_pk_mul_f32 v[8:9], v[14:15], v[8:9] op_sel_hi:[0,1]
	v_pk_mul_f32 v[12:13], v[14:15], v[18:19] op_sel_hi:[0,1]
	v_pk_mul_f32 v[14:15], v[14:15], v[28:29] op_sel_hi:[0,1]
	v_pk_mul_f32 v[10:11], v[10:11], v[34:35]
	v_pk_mul_f32 v[8:9], v[8:9], v[36:37]
	v_pk_mul_f32 v[12:13], v[12:13], v[38:39]
	v_pk_mul_f32 v[14:15], v[14:15], v[40:41]
	ds_swizzle_b32 v22, v10 offset:swizzle(SWAP,1)
	ds_swizzle_b32 v23, v10 offset:swizzle(SWAP,2)
	ds_swizzle_b32 v20, v8 offset:swizzle(SWAP,1)
	ds_swizzle_b32 v21, v8 offset:swizzle(SWAP,2)
	ds_swizzle_b32 v26, v11 offset:swizzle(SWAP,1)
	ds_swizzle_b32 v27, v11 offset:swizzle(SWAP,2)
	ds_swizzle_b32 v24, v9 offset:swizzle(SWAP,1)
	ds_swizzle_b32 v25, v9 offset:swizzle(SWAP,2)
	ds_swizzle_b32 v16, v12 offset:swizzle(SWAP,1)
	ds_swizzle_b32 v17, v12 offset:swizzle(SWAP,2)
	ds_swizzle_b32 v28, v14 offset:swizzle(SWAP,1)
	ds_swizzle_b32 v29, v14 offset:swizzle(SWAP,2)
	ds_swizzle_b32 v18, v13 offset:swizzle(SWAP,1)
	ds_swizzle_b32 v19, v13 offset:swizzle(SWAP,2)
	ds_swizzle_b32 v30, v15 offset:swizzle(SWAP,1)
	ds_swizzle_b32 v31, v15 offset:swizzle(SWAP,2)
	s_and_saveexec_b64 s[8:9], s[18:19]
	s_cbranch_execz .LBB0_369
	s_ashr_i32 s20, s27, 1
	s_cmpk_lt_u32 s20, 0x2000
	s_cselect_b32 s21, 4, 0
	s_lshr_b32 s27, s20, 7
	s_and_b32 s27, s27, 56
	s_or_b32 s21, s21, s27
	s_bfe_u32 s27, s20, 0x20008
	s_or_b32 s21, s21, s27
	s_lshl_b32 s21, s21, 8
	s_and_b32 s27, s20, 0xff
	s_or_b32 s21, s21, s27
	s_and_b32 s27, s21, s23
	s_lshr_b32 s28, s27, 6
	s_and_b32 s20, s20, 63
	v_mov_b32_e32 v44, s20
	v_mov_b32_e32 v45, s28
	v_cndmask_b32_e64 v44, v44, v45, s[0:1]
	v_mov_b32_e32 v45, s27
	v_cndmask_b32_e64 v44, v45, v44, s[10:11]
	v_cvt_f32_u32_e32 v44, v44
	s_waitcnt lgkmcnt(8)
	v_cndmask_b32_e64 v24, v24, v25, s[10:11]
	v_cndmask_b32_e64 v25, v20, v21, s[10:11]
	s_waitcnt lgkmcnt(6)
	v_cndmask_b32_e64 v71, v16, v17, s[10:11]
	v_mul_f32_e32 v20, v56, v44
	v_fract_f32_e32 v20, v20
	v_fmac_f32_e32 v20, v57, v44
	v_cos_f32_e32 v47, v20
	v_sin_f32_e32 v66, v20
	v_mul_f32_e32 v20, v58, v44
	v_fract_f32_e32 v20, v20
	v_fmac_f32_e32 v20, v59, v44
	v_cos_f32_e32 v67, v20
	v_sin_f32_e32 v68, v20
	v_mul_f32_e32 v20, v60, v44
	v_mul_f32_e32 v16, v62, v44
	v_mul_f32_e32 v45, v50, v44
	v_fract_f32_e32 v20, v20
	v_fract_f32_e32 v16, v16
	v_fract_f32_e32 v45, v45
	v_fmac_f32_e32 v20, v61, v44
	v_fmac_f32_e32 v16, v63, v44
	v_fmac_f32_e32 v45, v51, v44
	v_cos_f32_e32 v69, v20
	s_waitcnt lgkmcnt(2)
	v_cndmask_b32_e64 v70, v18, v19, s[10:11]
	v_sin_f32_e32 v72, v20
	v_cos_f32_e32 v18, v16
	v_sin_f32_e32 v20, v16
	v_mul_f32_e32 v16, v64, v44
	v_cndmask_b32_e64 v28, v28, v29, s[10:11]
	v_sin_f32_e32 v29, v45
	v_fract_f32_e32 v16, v16
	v_cos_f32_e32 v46, v45
	s_waitcnt lgkmcnt(0)
	v_cndmask_b32_e64 v30, v30, v31, s[10:11]
	v_mul_f32_e32 v31, v52, v44
	v_cndmask_b32_e64 v26, v26, v27, s[10:11]
	v_mul_f32_e32 v27, v54, v44
	v_fmac_f32_e32 v16, v65, v44
	v_fract_f32_e32 v31, v31
	v_fract_f32_e32 v27, v27
	v_sin_f32_e32 v73, v16
	v_fmac_f32_e32 v31, v53, v44
	v_fmac_f32_e32 v27, v55, v44
	v_cos_f32_e32 v44, v16
	v_cndmask_b32_e64 v22, v22, v23, s[10:11]
	v_sin_f32_e32 v23, v31
	v_cndmask_b32_e64 v16, 1.0, v18, s[4:5]
	v_cndmask_b32_e64 v18, v28, -v28, s[6:7]
	v_cndmask_b32_e64 v19, v30, -v30, s[6:7]
	v_cndmask_b32_e64 v21, 0, v29, s[4:5]
	v_cndmask_b32_e64 v20, 0, v20, s[4:5]
	v_cos_f32_e32 v45, v31
	v_cndmask_b32_e64 v17, 1.0, v46, s[4:5]
	v_pk_mul_f32 v[18:19], v[18:19], v[20:21]
	v_cos_f32_e32 v31, v27
	v_sin_f32_e32 v27, v27
	v_pk_fma_f32 v[14:15], v[14:15], v[16:17], v[18:19]
	v_cndmask_b32_e64 v18, v71, -v71, s[6:7]
	v_cndmask_b32_e64 v19, v70, -v70, s[6:7]
	v_cndmask_b32_e64 v21, 0, v73, s[4:5]
	v_cndmask_b32_e64 v20, 0, v72, s[4:5]
	v_cndmask_b32_e64 v17, 1.0, v44, s[4:5]
	v_cndmask_b32_e64 v16, 1.0, v69, s[4:5]
	v_pk_mul_f32 v[18:19], v[18:19], v[20:21]
	v_cndmask_b32_e64 v21, 0, v66, s[4:5]
	v_pk_fma_f32 v[12:13], v[12:13], v[16:17], v[18:19]
	v_cndmask_b32_e64 v18, v22, -v22, s[6:7]
	v_cndmask_b32_e64 v19, v26, -v26, s[6:7]
	v_cndmask_b32_e64 v20, 0, v23, s[4:5]
	v_cndmask_b32_e64 v17, 1.0, v47, s[4:5]
	v_cndmask_b32_e64 v16, 1.0, v45, s[4:5]
	v_pk_mul_f32 v[18:19], v[18:19], v[20:21]
	v_cndmask_b32_e64 v21, 0, v68, s[4:5]
	v_pk_fma_f32 v[10:11], v[10:11], v[16:17], v[18:19]
	v_cndmask_b32_e64 v18, v25, -v25, s[6:7]
	v_cndmask_b32_e64 v19, v24, -v24, s[6:7]
	v_cndmask_b32_e64 v20, 0, v27, s[4:5]
	v_cndmask_b32_e64 v17, 1.0, v67, s[4:5]
	v_cndmask_b32_e64 v16, 1.0, v31, s[4:5]
	v_pk_mul_f32 v[18:19], v[18:19], v[20:21]
	s_mov_b32 s20, 0xffff0000
	v_pk_fma_f32 v[8:9], v[8:9], v[16:17], v[18:19]
	v_cvt_pk_bf16_f32 v8, v10, v8
	v_cvt_pk_bf16_f32 v9, v11, v9
	v_cvt_pk_bf16_f32 v10, v12, v14
	v_cvt_pk_bf16_f32 v11, v13, v15
	s_mul_i32 s86, s21, 0x4200
	v_lshl_add_u64 v[12:13], v[42:43], 0, s[86:87]
	global_store_dwordx4 v[12:13], v[8:11], off

.LBB0_370:
	s_cmpk_gt_i32 s26, 0x7fff
	s_cbranch_scc1 .LBB0_374
	v_lshlrev_b32_e32 v8, 16, v4
	v_and_b32_e32 v4, 0xffff0000, v4
	v_lshlrev_b32_e32 v9, 16, v5
	v_and_b32_e32 v5, 0xffff0000, v5
	v_mov_b32_e32 v10, v8
	v_mov_b32_e32 v11, v4
	v_pk_mul_f32 v[10:11], v[10:11], v[10:11]
	v_mov_b32_e32 v12, v9
	v_mov_b32_e32 v13, v5
	v_pk_mul_f32 v[12:13], v[12:13], v[12:13]
	v_lshlrev_b32_e32 v14, 16, v6
	s_waitcnt lgkmcnt(7)
	v_and_b32_e32 v24, 0xffff0000, v6
	v_add_f32_e32 v10, v10, v11
	v_lshlrev_b32_e32 v15, 16, v7
	s_waitcnt lgkmcnt(6)
	v_and_b32_e32 v25, 0xffff0000, v7
	v_mov_b32_e32 v6, v14
	v_mov_b32_e32 v7, v24
	v_add_f32_e32 v10, v10, v12
	v_pk_mul_f32 v[6:7], v[6:7], v[6:7]
	v_add_f32_e32 v10, v10, v13
	v_mov_b32_e32 v16, v15
	v_mov_b32_e32 v17, v25
	v_add_f32_e32 v6, v10, v6
	v_pk_mul_f32 v[16:17], v[16:17], v[16:17]
	v_add_f32_e32 v6, v6, v7
	v_add_f32_e32 v6, v6, v16
	v_add_f32_e32 v6, v6, v17
	ds_swizzle_b32 v7, v6 offset:swizzle(SWAP,1)
	s_mov_b32 s8, 0x800000
	s_waitcnt lgkmcnt(0)
	v_add_f32_e32 v6, v6, v7
	ds_swizzle_b32 v7, v6 offset:swizzle(SWAP,2)
	s_waitcnt lgkmcnt(0)
	v_add_f32_e32 v6, v6, v7
	ds_swizzle_b32 v7, v6 offset:swizzle(SWAP,4)
	s_waitcnt lgkmcnt(0)
	v_add_f32_e32 v6, v6, v7
	v_fmamk_f32 v6, v6, 0x3c800000, v224
	v_mul_f32_e32 v7, 0x4b800000, v6
	v_cmp_gt_f32_e64 s[8:9], s8, v6
	s_nop 1
	v_cndmask_b32_e64 v6, v6, v7, s[8:9]
	v_rsq_f32_e32 v6, v6
	s_nop 0
	v_mul_f32_e32 v7, 0x45800000, v6
	v_cndmask_b32_e64 v10, v6, v7, s[8:9]
	v_pk_mul_f32 v[6:7], v[10:11], v[8:9] op_sel_hi:[0,1]
	v_pk_mul_f32 v[4:5], v[10:11], v[4:5] op_sel_hi:[0,1]
	v_pk_mul_f32 v[8:9], v[10:11], v[14:15] op_sel_hi:[0,1]
	v_pk_mul_f32 v[10:11], v[10:11], v[24:25] op_sel_hi:[0,1]
	v_pk_mul_f32 v[6:7], v[6:7], v[34:35]
	v_pk_mul_f32 v[4:5], v[4:5], v[36:37]
	v_pk_mul_f32 v[8:9], v[8:9], v[38:39]
	v_pk_mul_f32 v[10:11], v[10:11], v[40:41]
	ds_swizzle_b32 v18, v6 offset:swizzle(SWAP,1)
	ds_swizzle_b32 v19, v6 offset:swizzle(SWAP,2)
	ds_swizzle_b32 v16, v4 offset:swizzle(SWAP,1)
	ds_swizzle_b32 v17, v4 offset:swizzle(SWAP,2)
	ds_swizzle_b32 v22, v7 offset:swizzle(SWAP,1)
	ds_swizzle_b32 v23, v7 offset:swizzle(SWAP,2)
	ds_swizzle_b32 v20, v5 offset:swizzle(SWAP,1)
	ds_swizzle_b32 v21, v5 offset:swizzle(SWAP,2)
	ds_swizzle_b32 v12, v8 offset:swizzle(SWAP,1)
	ds_swizzle_b32 v13, v8 offset:swizzle(SWAP,2)
	ds_swizzle_b32 v24, v10 offset:swizzle(SWAP,1)
	ds_swizzle_b32 v25, v10 offset:swizzle(SWAP,2)
	ds_swizzle_b32 v14, v9 offset:swizzle(SWAP,1)
	ds_swizzle_b32 v15, v9 offset:swizzle(SWAP,2)
	ds_swizzle_b32 v26, v11 offset:swizzle(SWAP,1)
	ds_swizzle_b32 v27, v11 offset:swizzle(SWAP,2)
	s_and_saveexec_b64 s[8:9], s[18:19]
	s_cbranch_execz .LBB0_373
	s_ashr_i32 s20, s26, 1
	s_cmpk_lt_u32 s20, 0x2000
	s_cselect_b32 s21, 4, 0
	s_lshr_b32 s26, s20, 7
	s_and_b32 s26, s26, 56
	s_or_b32 s21, s21, s26
	s_bfe_u32 s26, s20, 0x20008
	s_or_b32 s21, s21, s26
	s_lshl_b32 s21, s21, 8
	s_and_b32 s26, s20, 0xff
	s_or_b32 s21, s21, s26
	s_and_b32 s26, s21, s23
	s_lshr_b32 s27, s26, 6
	s_and_b32 s20, s20, 63
	v_mov_b32_e32 v28, s20
	v_mov_b32_e32 v29, s27
	v_cndmask_b32_e64 v28, v28, v29, s[0:1]
	v_mov_b32_e32 v29, s26
	v_cndmask_b32_e64 v28, v29, v28, s[10:11]
	v_cvt_f32_u32_e32 v28, v28
	s_waitcnt lgkmcnt(8)
	v_cndmask_b32_e64 v20, v20, v21, s[10:11]
	v_cndmask_b32_e64 v21, v16, v17, s[10:11]
	s_waitcnt lgkmcnt(6)
	v_cndmask_b32_e64 v67, v12, v13, s[10:11]
	v_mul_f32_e32 v16, v56, v28
	v_fract_f32_e32 v16, v16
	v_fmac_f32_e32 v16, v57, v28
	v_cos_f32_e32 v31, v16
	v_sin_f32_e32 v44, v16
	v_mul_f32_e32 v16, v58, v28
	v_fract_f32_e32 v16, v16
	v_fmac_f32_e32 v16, v59, v28
	v_cos_f32_e32 v45, v16
	v_sin_f32_e32 v46, v16
	v_mul_f32_e32 v16, v60, v28
	v_mul_f32_e32 v12, v62, v28
	v_mul_f32_e32 v29, v50, v28
	v_fract_f32_e32 v16, v16
	v_fract_f32_e32 v12, v12
	v_fract_f32_e32 v29, v29
	v_fmac_f32_e32 v16, v61, v28
	v_fmac_f32_e32 v12, v63, v28
	v_fmac_f32_e32 v29, v51, v28
	v_cos_f32_e32 v47, v16
	s_waitcnt lgkmcnt(2)
	v_cndmask_b32_e64 v66, v14, v15, s[10:11]
	v_sin_f32_e32 v68, v16
	v_cos_f32_e32 v14, v12
	v_sin_f32_e32 v16, v12
	v_mul_f32_e32 v12, v64, v28
	v_cndmask_b32_e64 v24, v24, v25, s[10:11]
	v_sin_f32_e32 v25, v29
	v_fract_f32_e32 v12, v12
	v_cos_f32_e32 v30, v29
	s_waitcnt lgkmcnt(0)
	v_cndmask_b32_e64 v26, v26, v27, s[10:11]
	v_mul_f32_e32 v27, v52, v28
	v_cndmask_b32_e64 v22, v22, v23, s[10:11]
	v_mul_f32_e32 v23, v54, v28
	v_fmac_f32_e32 v12, v65, v28
	v_fract_f32_e32 v27, v27
	v_fract_f32_e32 v23, v23
	v_sin_f32_e32 v69, v12
	v_fmac_f32_e32 v27, v53, v28
	v_fmac_f32_e32 v23, v55, v28
	v_cos_f32_e32 v28, v12
	v_cndmask_b32_e64 v18, v18, v19, s[10:11]
	v_sin_f32_e32 v19, v27
	v_cndmask_b32_e64 v12, 1.0, v14, s[4:5]
	v_cndmask_b32_e64 v14, v24, -v24, s[6:7]
	v_cndmask_b32_e64 v15, v26, -v26, s[6:7]
	v_cndmask_b32_e64 v17, 0, v25, s[4:5]
	v_cndmask_b32_e64 v16, 0, v16, s[4:5]
	v_cos_f32_e32 v29, v27
	v_cndmask_b32_e64 v13, 1.0, v30, s[4:5]
	v_pk_mul_f32 v[14:15], v[14:15], v[16:17]
	v_cos_f32_e32 v27, v23
	v_sin_f32_e32 v23, v23
	v_pk_fma_f32 v[10:11], v[10:11], v[12:13], v[14:15]
	v_cndmask_b32_e64 v14, v67, -v67, s[6:7]
	v_cndmask_b32_e64 v15, v66, -v66, s[6:7]
	v_cndmask_b32_e64 v17, 0, v69, s[4:5]
	v_cndmask_b32_e64 v16, 0, v68, s[4:5]
	v_cndmask_b32_e64 v13, 1.0, v28, s[4:5]
	v_cndmask_b32_e64 v12, 1.0, v47, s[4:5]
	v_pk_mul_f32 v[14:15], v[14:15], v[16:17]
	v_cndmask_b32_e64 v17, 0, v44, s[4:5]
	v_pk_fma_f32 v[8:9], v[8:9], v[12:13], v[14:15]
	v_cndmask_b32_e64 v14, v18, -v18, s[6:7]
	v_cndmask_b32_e64 v15, v22, -v22, s[6:7]
	v_cndmask_b32_e64 v16, 0, v19, s[4:5]
	v_cndmask_b32_e64 v13, 1.0, v31, s[4:5]
	v_cndmask_b32_e64 v12, 1.0, v29, s[4:5]
	v_pk_mul_f32 v[14:15], v[14:15], v[16:17]
	v_cndmask_b32_e64 v17, 0, v46, s[4:5]
	v_pk_fma_f32 v[6:7], v[6:7], v[12:13], v[14:15]
	v_cndmask_b32_e64 v14, v21, -v21, s[6:7]
	v_cndmask_b32_e64 v15, v20, -v20, s[6:7]
	v_cndmask_b32_e64 v16, 0, v23, s[4:5]
	v_cndmask_b32_e64 v13, 1.0, v45, s[4:5]
	v_cndmask_b32_e64 v12, 1.0, v27, s[4:5]
	v_pk_mul_f32 v[14:15], v[14:15], v[16:17]
	s_mov_b32 s20, 0xffff0000
	v_pk_fma_f32 v[4:5], v[4:5], v[12:13], v[14:15]
	v_cvt_pk_bf16_f32 v4, v6, v4
	v_cvt_pk_bf16_f32 v5, v7, v5
	v_cvt_pk_bf16_f32 v6, v8, v10
	v_cvt_pk_bf16_f32 v7, v9, v11
	s_mul_i32 s86, s21, 0x4200
	v_lshl_add_u64 v[8:9], v[42:43], 0, s[86:87]
	global_store_dwordx4 v[8:9], v[4:7], off

.LBB0_374:
	s_cmpk_gt_i32 s25, 0x7fff
	s_cbranch_scc1 .LBB0_331
	v_lshlrev_b32_e32 v4, 16, v0
	v_and_b32_e32 v0, 0xffff0000, v0
	v_lshlrev_b32_e32 v5, 16, v1
	v_and_b32_e32 v1, 0xffff0000, v1
	v_mov_b32_e32 v6, v4
	v_mov_b32_e32 v7, v0
	v_pk_mul_f32 v[6:7], v[6:7], v[6:7]
	v_mov_b32_e32 v8, v5
	v_mov_b32_e32 v9, v1
	v_pk_mul_f32 v[8:9], v[8:9], v[8:9]
	v_lshlrev_b32_e32 v10, 16, v2
	s_waitcnt lgkmcnt(7)
	v_and_b32_e32 v20, 0xffff0000, v2
	v_add_f32_e32 v6, v6, v7
	v_lshlrev_b32_e32 v11, 16, v3
	s_waitcnt lgkmcnt(6)
	v_and_b32_e32 v21, 0xffff0000, v3
	v_mov_b32_e32 v2, v10
	v_mov_b32_e32 v3, v20
	v_add_f32_e32 v6, v6, v8
	v_pk_mul_f32 v[2:3], v[2:3], v[2:3]
	v_add_f32_e32 v6, v6, v9
	v_mov_b32_e32 v12, v11
	v_mov_b32_e32 v13, v21
	v_add_f32_e32 v2, v6, v2
	v_pk_mul_f32 v[12:13], v[12:13], v[12:13]
	v_add_f32_e32 v2, v2, v3
	v_add_f32_e32 v2, v2, v12
	v_add_f32_e32 v2, v2, v13
	ds_swizzle_b32 v3, v2 offset:swizzle(SWAP,1)
	s_mov_b32 s8, 0x800000
	s_waitcnt lgkmcnt(0)
	v_add_f32_e32 v2, v2, v3
	ds_swizzle_b32 v3, v2 offset:swizzle(SWAP,2)
	s_waitcnt lgkmcnt(0)
	v_add_f32_e32 v2, v2, v3
	ds_swizzle_b32 v3, v2 offset:swizzle(SWAP,4)
	s_waitcnt lgkmcnt(0)
	v_add_f32_e32 v2, v2, v3
	v_fmamk_f32 v2, v2, 0x3c800000, v224
	v_mul_f32_e32 v3, 0x4b800000, v2
	v_cmp_gt_f32_e64 s[8:9], s8, v2
	s_nop 1
	v_cndmask_b32_e64 v2, v2, v3, s[8:9]
	v_rsq_f32_e32 v2, v2
	s_nop 0
	v_mul_f32_e32 v3, 0x45800000, v2
	v_cndmask_b32_e64 v6, v2, v3, s[8:9]
	v_pk_mul_f32 v[2:3], v[6:7], v[4:5] op_sel_hi:[0,1]
	v_pk_mul_f32 v[0:1], v[6:7], v[0:1] op_sel_hi:[0,1]
	v_pk_mul_f32 v[4:5], v[6:7], v[10:11] op_sel_hi:[0,1]
	v_pk_mul_f32 v[6:7], v[6:7], v[20:21] op_sel_hi:[0,1]
	v_pk_mul_f32 v[2:3], v[2:3], v[34:35]
	v_pk_mul_f32 v[0:1], v[0:1], v[36:37]
	v_pk_mul_f32 v[4:5], v[4:5], v[38:39]
	v_pk_mul_f32 v[6:7], v[6:7], v[40:41]
	ds_swizzle_b32 v14, v2 offset:swizzle(SWAP,1)
	ds_swizzle_b32 v15, v2 offset:swizzle(SWAP,2)
	ds_swizzle_b32 v12, v0 offset:swizzle(SWAP,1)
	ds_swizzle_b32 v13, v0 offset:swizzle(SWAP,2)
	ds_swizzle_b32 v18, v3 offset:swizzle(SWAP,1)
	ds_swizzle_b32 v19, v3 offset:swizzle(SWAP,2)
	ds_swizzle_b32 v16, v1 offset:swizzle(SWAP,1)
	ds_swizzle_b32 v17, v1 offset:swizzle(SWAP,2)
	ds_swizzle_b32 v8, v4 offset:swizzle(SWAP,1)
	ds_swizzle_b32 v9, v4 offset:swizzle(SWAP,2)
	ds_swizzle_b32 v20, v6 offset:swizzle(SWAP,1)
	ds_swizzle_b32 v21, v6 offset:swizzle(SWAP,2)
	ds_swizzle_b32 v10, v5 offset:swizzle(SWAP,1)
	ds_swizzle_b32 v11, v5 offset:swizzle(SWAP,2)
	ds_swizzle_b32 v22, v7 offset:swizzle(SWAP,1)
	ds_swizzle_b32 v23, v7 offset:swizzle(SWAP,2)
	s_and_saveexec_b64 s[8:9], s[18:19]
	s_cbranch_execz .LBB0_330
	s_ashr_i32 s20, s25, 1
	s_cmpk_lt_u32 s20, 0x2000
	s_cselect_b32 s21, 4, 0
	s_lshr_b32 s25, s20, 7
	s_and_b32 s25, s25, 56
	s_or_b32 s21, s21, s25
	s_bfe_u32 s25, s20, 0x20008
	s_or_b32 s21, s21, s25
	s_lshl_b32 s21, s21, 8
	s_and_b32 s25, s20, 0xff
	s_or_b32 s21, s21, s25
	s_and_b32 s25, s21, s23
	s_lshr_b32 s26, s25, 6
	s_and_b32 s20, s20, 63
	v_mov_b32_e32 v24, s20
	v_mov_b32_e32 v25, s26
	v_cndmask_b32_e64 v24, v24, v25, s[0:1]
	v_mov_b32_e32 v25, s25
	v_cndmask_b32_e64 v24, v25, v24, s[10:11]
	v_cvt_f32_u32_e32 v24, v24
	s_waitcnt lgkmcnt(8)
	v_cndmask_b32_e64 v16, v16, v17, s[10:11]
	v_cndmask_b32_e64 v17, v12, v13, s[10:11]
	s_waitcnt lgkmcnt(6)
	v_cndmask_b32_e64 v45, v8, v9, s[10:11]
	v_mul_f32_e32 v12, v56, v24
	v_fract_f32_e32 v12, v12
	v_fmac_f32_e32 v12, v57, v24
	v_cos_f32_e32 v27, v12
	v_sin_f32_e32 v28, v12
	v_mul_f32_e32 v12, v58, v24
	v_fract_f32_e32 v12, v12
	v_fmac_f32_e32 v12, v59, v24
	v_cos_f32_e32 v29, v12
	v_sin_f32_e32 v30, v12
	v_mul_f32_e32 v12, v60, v24
	v_mul_f32_e32 v8, v62, v24
	v_mul_f32_e32 v25, v50, v24
	v_fract_f32_e32 v12, v12
	v_fract_f32_e32 v8, v8
	v_fract_f32_e32 v25, v25
	v_fmac_f32_e32 v12, v61, v24
	v_fmac_f32_e32 v8, v63, v24
	v_fmac_f32_e32 v25, v51, v24
	v_cos_f32_e32 v31, v12
	s_waitcnt lgkmcnt(2)
	v_cndmask_b32_e64 v44, v10, v11, s[10:11]
	v_sin_f32_e32 v46, v12
	v_cos_f32_e32 v10, v8
	v_sin_f32_e32 v12, v8
	v_mul_f32_e32 v8, v64, v24
	v_cndmask_b32_e64 v20, v20, v21, s[10:11]
	v_sin_f32_e32 v21, v25
	v_fract_f32_e32 v8, v8
	v_cos_f32_e32 v26, v25
	s_waitcnt lgkmcnt(0)
	v_cndmask_b32_e64 v22, v22, v23, s[10:11]
	v_mul_f32_e32 v23, v52, v24
	v_cndmask_b32_e64 v18, v18, v19, s[10:11]
	v_mul_f32_e32 v19, v54, v24
	v_fmac_f32_e32 v8, v65, v24
	v_fract_f32_e32 v23, v23
	v_fract_f32_e32 v19, v19
	v_sin_f32_e32 v47, v8
	v_fmac_f32_e32 v23, v53, v24
	v_fmac_f32_e32 v19, v55, v24
	v_cos_f32_e32 v24, v8
	v_cndmask_b32_e64 v14, v14, v15, s[10:11]
	v_sin_f32_e32 v15, v23
	v_cndmask_b32_e64 v8, 1.0, v10, s[4:5]
	v_cndmask_b32_e64 v10, v20, -v20, s[6:7]
	v_cndmask_b32_e64 v11, v22, -v22, s[6:7]
	v_cndmask_b32_e64 v13, 0, v21, s[4:5]
	v_cndmask_b32_e64 v12, 0, v12, s[4:5]
	v_cos_f32_e32 v25, v23
	v_cndmask_b32_e64 v9, 1.0, v26, s[4:5]
	v_pk_mul_f32 v[10:11], v[10:11], v[12:13]
	v_cos_f32_e32 v23, v19
	v_sin_f32_e32 v19, v19
	v_pk_fma_f32 v[6:7], v[6:7], v[8:9], v[10:11]
	v_cndmask_b32_e64 v10, v45, -v45, s[6:7]
	v_cndmask_b32_e64 v11, v44, -v44, s[6:7]
	v_cndmask_b32_e64 v13, 0, v47, s[4:5]
	v_cndmask_b32_e64 v12, 0, v46, s[4:5]
	v_cndmask_b32_e64 v9, 1.0, v24, s[4:5]
	v_cndmask_b32_e64 v8, 1.0, v31, s[4:5]
	v_pk_mul_f32 v[10:11], v[10:11], v[12:13]
	v_cndmask_b32_e64 v13, 0, v28, s[4:5]
	v_pk_fma_f32 v[4:5], v[4:5], v[8:9], v[10:11]
	v_cndmask_b32_e64 v10, v14, -v14, s[6:7]
	v_cndmask_b32_e64 v11, v18, -v18, s[6:7]
	v_cndmask_b32_e64 v12, 0, v15, s[4:5]
	v_cndmask_b32_e64 v9, 1.0, v27, s[4:5]
	v_cndmask_b32_e64 v8, 1.0, v25, s[4:5]
	v_pk_mul_f32 v[10:11], v[10:11], v[12:13]
	v_cndmask_b32_e64 v13, 0, v30, s[4:5]
	v_pk_fma_f32 v[2:3], v[2:3], v[8:9], v[10:11]
	v_cndmask_b32_e64 v10, v17, -v17, s[6:7]
	v_cndmask_b32_e64 v11, v16, -v16, s[6:7]
	v_cndmask_b32_e64 v12, 0, v19, s[4:5]
	v_cndmask_b32_e64 v9, 1.0, v29, s[4:5]
	v_cndmask_b32_e64 v8, 1.0, v23, s[4:5]
	v_pk_mul_f32 v[10:11], v[10:11], v[12:13]
	s_mov_b32 s20, 0xffff0000
	v_pk_fma_f32 v[0:1], v[0:1], v[8:9], v[10:11]
	v_cvt_pk_bf16_f32 v0, v2, v0
	v_cvt_pk_bf16_f32 v1, v3, v1
	v_cvt_pk_bf16_f32 v2, v4, v6
	v_cvt_pk_bf16_f32 v3, v5, v7
	s_mul_i32 s86, s21, 0x4200
	v_lshl_add_u64 v[4:5], v[42:43], 0, s[86:87]
	global_store_dwordx4 v[4:5], v[0:3], off
	s_branch .LBB0_330
